# LN, group-norm and prologue row loops: per-token counted vmcnt waits instead of draining all four tokens' loads first
# speedup vs baseline: 1.0039x; 1.0039x over previous
; __device__ __forceinline__ void phase_ln(bf16* X, const bf16* Mx, const float* g, const float* b, int tid) {
;     ...
;         for (int u = 0; u < 4; ++u) { const int t = t0 + u * NGW; if (t < T) {
;             float x[16], m[16];
;             unpack8(xa[u][0], x); unpack8(xa[u][1], x + 8); unpack8(ma[u][0], m); unpack8(ma[u][1], m + 8);
;             float sum = 0.f;
; #pragma unroll
;             for (int i = 0; i < 16; ++i) { x[i] = ALPHA * x[i] + m[i]; sum += x[i]; }
;             const float mean = wave_sum(sum) * (1.f / DM);
;             float q = 0.f;
; #pragma unroll
;             for (int i = 0; i < 16; ++i) { x[i] -= mean; q += x[i] * x[i]; }
;             const float rstd = rsqrtf(wave_sum(q) * (1.f / DM) + LN_EPS);
.LBB0_159:
	s_or_b64 exec, exec, s[36:37]
	s_cbranch_vccnz .Lln_fast
	s_waitcnt vmcnt(0)
.Lln_fast:
	s_waitcnt vmcnt(15)
	v_lshlrev_b32_e32 v117, 16, v93
	v_lshlrev_b32_e32 v116, 16, v92
	s_waitcnt vmcnt(13)
	v_lshlrev_b32_e32 v122, 16, v88
	v_lshlrev_b32_e32 v123, 16, v89
	v_and_b32_e32 v128, 0xffff0000, v86
	v_lshlrev_b32_e32 v129, 16, v86
	s_waitcnt vmcnt(12)
	v_and_b32_e32 v130, 0xffff0000, v82
	v_lshlrev_b32_e32 v131, 16, v82
	s_mov_b32 s14, 0x3fb504f3
	v_and_b32_e32 v86, 0xffff0000, v87
	v_lshlrev_b32_e32 v87, 16, v87
	v_and_b32_e32 v82, 0xffff0000, v83
	v_lshlrev_b32_e32 v83, 16, v83
	v_and_b32_e32 v93, 0xffff0000, v93
	v_and_b32_e32 v92, 0xffff0000, v92
	v_and_b32_e32 v88, 0xffff0000, v88
	v_and_b32_e32 v89, 0xffff0000, v89
	v_pk_fma_f32 v[82:83], v[86:87], s[14:15], v[82:83] op_sel_hi:[1,0,1]
	v_pk_fma_f32 v[86:87], v[116:117], s[14:15], v[122:123] op_sel_hi:[1,0,1]
	v_pk_fma_f32 v[88:89], v[92:93], s[14:15], v[88:89] op_sel_hi:[1,0,1]
	v_add_f32_e32 v115, 0, v86
	v_add_f32_e32 v92, v88, v115
	v_lshlrev_b32_e32 v119, 16, v95
	v_lshlrev_b32_e32 v118, 16, v94
	v_lshlrev_b32_e32 v124, 16, v90
	v_lshlrev_b32_e32 v125, 16, v91
	v_add_f32_e32 v92, v87, v92
	v_and_b32_e32 v95, 0xffff0000, v95
	v_and_b32_e32 v94, 0xffff0000, v94
	v_and_b32_e32 v90, 0xffff0000, v90
	v_and_b32_e32 v91, 0xffff0000, v91
	v_add_f32_e32 v115, v89, v92
	v_pk_fma_f32 v[92:93], v[118:119], s[14:15], v[124:125] op_sel_hi:[1,0,1]
	v_pk_fma_f32 v[90:91], v[94:95], s[14:15], v[90:91] op_sel_hi:[1,0,1]
	v_add_f32_e32 v94, v92, v115
	v_add_f32_e32 v94, v90, v94
	v_lshlrev_b32_e32 v121, 16, v85
	v_lshlrev_b32_e32 v120, 16, v84
	v_lshlrev_b32_e32 v126, 16, v80
	v_lshlrev_b32_e32 v127, 16, v81
	v_add_f32_e32 v94, v93, v94
	v_and_b32_e32 v85, 0xffff0000, v85
	v_and_b32_e32 v84, 0xffff0000, v84
	v_and_b32_e32 v80, 0xffff0000, v80
	v_and_b32_e32 v81, 0xffff0000, v81
	v_add_f32_e32 v115, v91, v94
	v_pk_fma_f32 v[94:95], v[120:121], s[14:15], v[126:127] op_sel_hi:[1,0,1]
	v_pk_fma_f32 v[80:81], v[84:85], s[14:15], v[80:81] op_sel_hi:[1,0,1]
	v_add_f32_e32 v84, v94, v115
	v_add_f32_e32 v84, v80, v84
	v_add_f32_e32 v84, v95, v84
	v_pk_fma_f32 v[128:129], v[128:129], s[14:15], v[130:131] op_sel_hi:[1,0,1]
	v_add_f32_e32 v84, v81, v84
	v_add_f32_e32 v84, v129, v84
	v_add_f32_e32 v84, v128, v84
	v_add_f32_e32 v84, v83, v84
	v_add_f32_e32 v84, v82, v84
	v_mov_b32_e32 v130, v129
	v_mov_b32_e32 v131, v83
	v_mov_b32_e32 v129, v82
	s_mov_b32 s9, 0x800000
	s_waitcnt lgkmcnt(0)
	s_nop 1
	v_add_f32_dpp v84, v84, v84 quad_perm:[1,0,3,2] row_mask:0xf bank_mask:0xf
	s_waitcnt lgkmcnt(0)
	s_nop 1
	v_add_f32_dpp v84, v84, v84 quad_perm:[2,3,0,1] row_mask:0xf bank_mask:0xf
	s_waitcnt lgkmcnt(0)
	s_nop 1
	v_add_f32_dpp v84, v84, v84 row_half_mirror row_mask:0xf bank_mask:0xf
	s_waitcnt lgkmcnt(0)
	s_nop 1
	v_add_f32_dpp v84, v84, v84 row_mirror row_mask:0xf bank_mask:0xf
	s_waitcnt lgkmcnt(0)
	v_mov_b32_e32 v85, v84
	s_nop 1
	v_permlane16_swap_b32_e32 v84, v85
	v_add_f32_e32 v84, v84, v85
	s_waitcnt lgkmcnt(0)
	v_mov_b32_e32 v85, v84
	s_nop 1
	v_permlane32_swap_b32_e32 v84, v85
	v_add_f32_e32 v84, v84, v85
	v_mul_f32_e32 v84, 0x3a800000, v84
	v_pk_add_f32 v[86:87], v[86:87], v[84:85] op_sel_hi:[1,0] neg_lo:[0,1] neg_hi:[0,1]
	v_pk_add_f32 v[88:89], v[88:89], v[84:85] op_sel_hi:[1,0] neg_lo:[0,1] neg_hi:[0,1]
	v_pk_mul_f32 v[116:117], v[86:87], v[86:87]
	v_pk_mul_f32 v[118:119], v[88:89], v[88:89]
	v_pk_add_f32 v[92:93], v[92:93], v[84:85] op_sel_hi:[1,0] neg_lo:[0,1] neg_hi:[0,1]
	v_add_f32_e32 v115, v116, v118
	v_add_f32_e32 v115, v117, v115
	v_pk_mul_f32 v[120:121], v[92:93], v[92:93]
	v_pk_add_f32 v[90:91], v[90:91], v[84:85] op_sel_hi:[1,0] neg_lo:[0,1] neg_hi:[0,1]
	v_add_f32_e32 v115, v119, v115
	v_pk_mul_f32 v[122:123], v[90:91], v[90:91]
	v_add_f32_e32 v115, v120, v115
	v_add_f32_e32 v115, v122, v115
	v_pk_add_f32 v[94:95], v[94:95], v[84:85] op_sel_hi:[1,0] neg_lo:[0,1] neg_hi:[0,1]
	v_add_f32_e32 v115, v121, v115
	v_pk_mul_f32 v[124:125], v[94:95], v[94:95]
	v_pk_add_f32 v[80:81], v[80:81], v[84:85] op_sel_hi:[1,0] neg_lo:[0,1] neg_hi:[0,1]
	v_add_f32_e32 v115, v123, v115
	v_pk_mul_f32 v[126:127], v[80:81], v[80:81]
	v_add_f32_e32 v115, v124, v115
	v_pk_add_f32 v[130:131], v[130:131], v[84:85] op_sel_hi:[1,0] neg_lo:[0,1] neg_hi:[0,1]
	v_pk_add_f32 v[82:83], v[128:129], v[84:85] op_sel_hi:[1,0] neg_lo:[0,1] neg_hi:[0,1]
	v_add_f32_e32 v115, v126, v115
	v_mov_b32_e32 v84, v82
	v_mov_b32_e32 v85, v130
	v_add_f32_e32 v115, v125, v115
	v_pk_mul_f32 v[84:85], v[84:85], v[84:85]
	v_add_f32_e32 v115, v127, v115
	v_mov_b32_e32 v128, v83
	v_mov_b32_e32 v129, v131
	v_add_f32_e32 v85, v85, v115
	v_pk_mul_f32 v[128:129], v[128:129], v[128:129]
	v_add_f32_e32 v84, v84, v85
	v_add_f32_e32 v84, v129, v84
	v_add_f32_e32 v84, v128, v84
	s_waitcnt lgkmcnt(0)
	s_nop 1
	v_add_f32_dpp v84, v84, v84 quad_perm:[1,0,3,2] row_mask:0xf bank_mask:0xf
	s_waitcnt lgkmcnt(0)
	s_nop 1
	v_add_f32_dpp v84, v84, v84 quad_perm:[2,3,0,1] row_mask:0xf bank_mask:0xf
	s_waitcnt lgkmcnt(0)
	s_nop 1
	v_add_f32_dpp v84, v84, v84 row_half_mirror row_mask:0xf bank_mask:0xf
	s_waitcnt lgkmcnt(0)
	s_nop 1
	v_add_f32_dpp v84, v84, v84 row_mirror row_mask:0xf bank_mask:0xf
	s_waitcnt lgkmcnt(0)
	v_mov_b32_e32 v85, v84
	s_nop 1
	v_permlane16_swap_b32_e32 v84, v85
	v_add_f32_e32 v84, v84, v85
	s_waitcnt lgkmcnt(0)
; __device__ __forceinline__ void phase_ln(bf16* X, const bf16* Mx, const float* g, const float* b, int tid) {
;     ...
;         for (int u = 0; u < 4; ++u) { const int t = t0 + u * NGW; if (t < T) {
;             float x[16], m[16];
;             unpack8(xa[u][0], x); unpack8(xa[u][1], x + 8); unpack8(ma[u][0], m); unpack8(ma[u][1], m + 8);
;             float sum = 0.f;
; #pragma unroll
;             for (int i = 0; i < 16; ++i) { x[i] = ALPHA * x[i] + m[i]; sum += x[i]; }
;             const float mean = wave_sum(sum) * (1.f / DM);
;             float q = 0.f;
; #pragma unroll
;             for (int i = 0; i < 16; ++i) { x[i] -= mean; q += x[i] * x[i]; }
;             const float rstd = rsqrtf(wave_sum(q) * (1.f / DM) + LN_EPS);
; #pragma unroll
;             for (int i = 0; i < 16; ++i) x[i] = x[i] * rstd * gg[i] + bb[i];
;             store_row_bf16(X + (size_t)t * DM, lane, x); } }
	v_mov_b32_e32 v85, v84
	s_nop 1
	v_permlane32_swap_b32_e32 v84, v85
	v_add_f32_e32 v84, v84, v85
	v_fmamk_f32 v84, v84, 0x3a800000, v164
	v_mul_f32_e32 v85, 0x4b800000, v84
	v_cmp_gt_f32_e64 s[44:45], s9, v84
	s_nop 1
	v_cndmask_b32_e64 v84, v84, v85, s[44:45]
	v_rsq_f32_e32 v84, v84
	s_nop 0
	v_mul_f32_e32 v85, 0x45800000, v84
	v_cndmask_b32_e64 v84, v84, v85, s[44:45]
	v_pk_mul_f32 v[80:81], v[80:81], v[84:85] op_sel_hi:[1,0]
	v_pk_mul_f32 v[88:89], v[88:89], v[84:85] op_sel_hi:[1,0]
	v_pk_mul_f32 v[90:91], v[90:91], v[84:85] op_sel_hi:[1,0]
	v_pk_fma_f32 v[116:117], v[28:29], v[80:81], v[12:13]
	v_pk_mul_f32 v[80:81], v[130:131], v[84:85] op_sel_hi:[1,0]
	v_pk_mul_f32 v[86:87], v[86:87], v[84:85] op_sel_hi:[1,0]
	v_pk_fma_f32 v[88:89], v[98:99], v[88:89], v[96:97]
	v_pk_mul_f32 v[92:93], v[92:93], v[84:85] op_sel_hi:[1,0]
	v_pk_fma_f32 v[90:91], v[100:101], v[90:91], v[16:17]
	v_pk_fma_f32 v[118:119], v[18:19], v[80:81], v[2:3]
	v_pk_mul_f32 v[80:81], v[82:83], v[84:85] op_sel_hi:[1,0]
	v_pk_fma_f32 v[86:87], v[30:31], v[86:87], v[14:15]
	v_pk_fma_f32 v[92:93], v[26:27], v[92:93], v[10:11]
	v_pk_mul_f32 v[94:95], v[94:95], v[84:85] op_sel_hi:[1,0]
	v_pk_fma_f32 v[84:85], v[24:25], v[80:81], v[8:9]
	v_bfe_u32 v80, v91, 16, 1
	v_bfe_u32 v81, v90, 16, 1
	v_bfe_u32 v82, v89, 16, 1
	v_bfe_u32 v83, v88, 16, 1
	v_add3_u32 v88, v88, v83, s84
	v_add3_u32 v89, v89, v82, s84
	v_add3_u32 v81, v90, v81, s84
	v_add3_u32 v80, v91, v80, s84
	v_bfe_u32 v82, v86, 16, 1
	v_bfe_u32 v83, v87, 16, 1
	v_bfe_u32 v90, v92, 16, 1
	v_bfe_u32 v91, v93, 16, 1
	v_add3_u32 v91, v93, v91, s84
	v_add3_u32 v90, v92, v90, s84
	v_add3_u32 v83, v87, v83, s84
	v_add3_u32 v82, v86, v82, s84
	v_lshrrev_b32_e32 v86, 16, v82
	v_lshrrev_b32_e32 v87, 16, v83
	v_lshrrev_b32_e32 v82, 16, v90
	v_lshrrev_b32_e32 v83, 16, v91
	v_and_or_b32 v83, v80, s3, v83
	v_and_or_b32 v82, v81, s3, v82
	v_and_or_b32 v81, v89, s3, v87
	v_and_or_b32 v80, v88, s3, v86
	v_pk_fma_f32 v[94:95], v[22:23], v[94:95], v[6:7]
	global_store_dwordx4 v[108:109], v[80:83], off
	s_nop 1
	v_bfe_u32 v80, v85, 16, 1
	v_bfe_u32 v81, v84, 16, 1
	v_bfe_u32 v82, v117, 16, 1
	v_bfe_u32 v83, v116, 16, 1
	v_add3_u32 v86, v116, v83, s84
	v_add3_u32 v87, v117, v82, s84
	v_add3_u32 v81, v84, v81, s84
	v_add3_u32 v80, v85, v80, s84
	v_bfe_u32 v82, v94, 16, 1
	v_bfe_u32 v83, v95, 16, 1
	v_bfe_u32 v84, v118, 16, 1
	v_bfe_u32 v85, v119, 16, 1
	v_add3_u32 v85, v119, v85, s84
	v_add3_u32 v84, v118, v84, s84
	v_add3_u32 v83, v95, v83, s84
	v_add3_u32 v82, v94, v82, s84
	v_lshrrev_b32_e32 v88, 16, v82
	v_lshrrev_b32_e32 v89, 16, v83
	v_lshrrev_b32_e32 v82, 16, v84
	v_lshrrev_b32_e32 v83, 16, v85
	v_and_or_b32 v83, v80, s3, v83
	v_and_or_b32 v82, v81, s3, v82
	v_and_or_b32 v81, v87, s3, v89
	v_and_or_b32 v80, v86, s3, v88
	global_store_dwordx4 v[108:109], v[80:83], off offset:1024
	s_and_saveexec_b64 s[36:37], s[42:43]
	s_cbranch_execz .LBB0_162
	s_waitcnt vmcnt(10)
	v_lshlrev_b32_e32 v81, 16, v53
	v_lshlrev_b32_e32 v80, 16, v52
	v_lshlrev_b32_e32 v92, 16, v76
	v_lshlrev_b32_e32 v93, 16, v77
	v_and_b32_e32 v83, 0xffff0000, v53
	v_and_b32_e32 v82, 0xffff0000, v52
	v_and_b32_e32 v94, 0xffff0000, v76
	v_and_b32_e32 v95, 0xffff0000, v77
	v_pk_fma_f32 v[80:81], v[80:81], s[14:15], v[92:93] op_sel_hi:[1,0,1]
	v_pk_fma_f32 v[82:83], v[82:83], s[14:15], v[94:95] op_sel_hi:[1,0,1]
	v_add_f32_e32 v92, 0, v80
	v_add_f32_e32 v92, v82, v92
	v_lshlrev_b32_e32 v85, 16, v55
	v_lshlrev_b32_e32 v84, 16, v54
	v_lshlrev_b32_e32 v108, 16, v78
	v_lshlrev_b32_e32 v109, 16, v79
	v_add_f32_e32 v92, v81, v92
	v_and_b32_e32 v87, 0xffff0000, v55
	v_and_b32_e32 v86, 0xffff0000, v54
	v_and_b32_e32 v116, 0xffff0000, v78
	v_and_b32_e32 v117, 0xffff0000, v79
	v_add_f32_e32 v92, v83, v92
	v_pk_fma_f32 v[84:85], v[84:85], s[14:15], v[108:109] op_sel_hi:[1,0,1]
	v_pk_fma_f32 v[86:87], v[86:87], s[14:15], v[116:117] op_sel_hi:[1,0,1]
	v_add_f32_e32 v92, v84, v92
	v_add_f32_e32 v92, v86, v92
	v_lshlrev_b32_e32 v89, 16, v49
	v_lshlrev_b32_e32 v88, 16, v48
	v_lshlrev_b32_e32 v118, 16, v72
	v_lshlrev_b32_e32 v119, 16, v73
	v_add_f32_e32 v92, v85, v92
	v_and_b32_e32 v91, 0xffff0000, v49
	v_and_b32_e32 v90, 0xffff0000, v48
	v_and_b32_e32 v120, 0xffff0000, v72
	v_and_b32_e32 v121, 0xffff0000, v73
	v_add_f32_e32 v92, v87, v92
	v_pk_fma_f32 v[88:89], v[88:89], s[14:15], v[118:119] op_sel_hi:[1,0,1]
	v_pk_fma_f32 v[90:91], v[90:91], s[14:15], v[120:121] op_sel_hi:[1,0,1]
	v_add_f32_e32 v92, v88, v92
	v_add_f32_e32 v92, v90, v92
	v_and_b32_e32 v122, 0xffff0000, v50
	v_lshlrev_b32_e32 v123, 16, v50
	v_and_b32_e32 v124, 0xffff0000, v74
	v_lshlrev_b32_e32 v125, 16, v74
	v_add_f32_e32 v92, v89, v92
	v_pk_fma_f32 v[122:123], v[122:123], s[14:15], v[124:125] op_sel_hi:[1,0,1]
	v_add_f32_e32 v92, v91, v92
	v_and_b32_e32 v124, 0xffff0000, v51
	v_lshlrev_b32_e32 v125, 16, v51
	v_and_b32_e32 v126, 0xffff0000, v75
	v_lshlrev_b32_e32 v127, 16, v75
	v_add_f32_e32 v92, v123, v92
	v_pk_fma_f32 v[124:125], v[124:125], s[14:15], v[126:127] op_sel_hi:[1,0,1]
	v_add_f32_e32 v92, v122, v92
	v_add_f32_e32 v92, v125, v92
	v_add_f32_e32 v92, v124, v92
	v_mov_b32_e32 v128, v123
	v_mov_b32_e32 v129, v125
	v_mov_b32_e32 v123, v124
	s_waitcnt lgkmcnt(0)
	s_nop 1
	v_add_f32_dpp v92, v92, v92 quad_perm:[1,0,3,2] row_mask:0xf bank_mask:0xf
	s_waitcnt lgkmcnt(0)
	s_nop 1
	v_add_f32_dpp v92, v92, v92 quad_perm:[2,3,0,1] row_mask:0xf bank_mask:0xf
	s_waitcnt lgkmcnt(0)
	s_nop 1
	v_add_f32_dpp v92, v92, v92 row_half_mirror row_mask:0xf bank_mask:0xf
	s_waitcnt lgkmcnt(0)
; __device__ __forceinline__ void phase_ln(bf16* X, const bf16* Mx, const float* g, const float* b, int tid) {
;     ...
;             const float mean = wave_sum(sum) * (1.f / DM);
;             float q = 0.f;
; #pragma unroll
;             for (int i = 0; i < 16; ++i) { x[i] -= mean; q += x[i] * x[i]; }
;             const float rstd = rsqrtf(wave_sum(q) * (1.f / DM) + LN_EPS);
; #pragma unroll
;             for (int i = 0; i < 16; ++i) x[i] = x[i] * rstd * gg[i] + bb[i];
;             store_row_bf16(X + (size_t)t * DM, lane, x); } }
	s_nop 1
	v_add_f32_dpp v92, v92, v92 row_mirror row_mask:0xf bank_mask:0xf
	s_waitcnt lgkmcnt(0)
	v_mov_b32_e32 v93, v92
	s_nop 1
	v_permlane16_swap_b32_e32 v92, v93
	v_add_f32_e32 v92, v92, v93
	s_waitcnt lgkmcnt(0)
	v_mov_b32_e32 v93, v92
	s_nop 1
	v_permlane32_swap_b32_e32 v92, v93
	v_add_f32_e32 v92, v92, v93
	v_mul_f32_e32 v92, 0x3a800000, v92
	v_pk_add_f32 v[80:81], v[80:81], v[92:93] op_sel_hi:[1,0] neg_lo:[0,1] neg_hi:[0,1]
	v_pk_add_f32 v[82:83], v[82:83], v[92:93] op_sel_hi:[1,0] neg_lo:[0,1] neg_hi:[0,1]
	v_pk_mul_f32 v[94:95], v[80:81], v[80:81]
	v_pk_mul_f32 v[108:109], v[82:83], v[82:83]
	v_pk_add_f32 v[84:85], v[84:85], v[92:93] op_sel_hi:[1,0] neg_lo:[0,1] neg_hi:[0,1]
	v_add_f32_e32 v94, v94, v108
	v_add_f32_e32 v94, v95, v94
	v_pk_mul_f32 v[116:117], v[84:85], v[84:85]
	v_pk_add_f32 v[86:87], v[86:87], v[92:93] op_sel_hi:[1,0] neg_lo:[0,1] neg_hi:[0,1]
	v_add_f32_e32 v94, v109, v94
	v_pk_mul_f32 v[118:119], v[86:87], v[86:87]
	v_add_f32_e32 v94, v116, v94
	v_add_f32_e32 v94, v118, v94
	v_pk_add_f32 v[88:89], v[88:89], v[92:93] op_sel_hi:[1,0] neg_lo:[0,1] neg_hi:[0,1]
	v_add_f32_e32 v94, v117, v94
	v_pk_mul_f32 v[120:121], v[88:89], v[88:89]
	v_pk_add_f32 v[90:91], v[90:91], v[92:93] op_sel_hi:[1,0] neg_lo:[0,1] neg_hi:[0,1]
	v_add_f32_e32 v94, v119, v94
	v_pk_mul_f32 v[126:127], v[90:91], v[90:91]
	v_add_f32_e32 v94, v120, v94
	v_pk_add_f32 v[128:129], v[128:129], v[92:93] op_sel_hi:[1,0] neg_lo:[0,1] neg_hi:[0,1]
	v_pk_add_f32 v[92:93], v[122:123], v[92:93] op_sel_hi:[1,0] neg_lo:[0,1] neg_hi:[0,1]
	v_add_f32_e32 v94, v126, v94
	v_mov_b32_e32 v122, v92
	v_mov_b32_e32 v123, v128
	v_add_f32_e32 v94, v121, v94
	v_pk_mul_f32 v[122:123], v[122:123], v[122:123]
	v_add_f32_e32 v94, v127, v94
	v_mov_b32_e32 v124, v93
	v_mov_b32_e32 v125, v129
	v_add_f32_e32 v94, v123, v94
	v_pk_mul_f32 v[124:125], v[124:125], v[124:125]
	v_add_f32_e32 v94, v122, v94
	v_add_f32_e32 v94, v125, v94
	v_add_f32_e32 v94, v124, v94
	s_waitcnt lgkmcnt(0)
	s_nop 1
	v_add_f32_dpp v94, v94, v94 quad_perm:[1,0,3,2] row_mask:0xf bank_mask:0xf
	s_waitcnt lgkmcnt(0)
	s_nop 1
	v_add_f32_dpp v94, v94, v94 quad_perm:[2,3,0,1] row_mask:0xf bank_mask:0xf
	s_waitcnt lgkmcnt(0)
	s_nop 1
	v_add_f32_dpp v94, v94, v94 row_half_mirror row_mask:0xf bank_mask:0xf
	s_waitcnt lgkmcnt(0)
	s_nop 1
	v_add_f32_dpp v94, v94, v94 row_mirror row_mask:0xf bank_mask:0xf
	s_waitcnt lgkmcnt(0)
	v_mov_b32_e32 v95, v94
	s_nop 1
	v_permlane16_swap_b32_e32 v94, v95
	v_add_f32_e32 v94, v94, v95
	s_waitcnt lgkmcnt(0)
	v_mov_b32_e32 v95, v94
	s_nop 1
	v_permlane32_swap_b32_e32 v94, v95
	v_add_f32_e32 v94, v94, v95
	v_fmamk_f32 v94, v94, 0x3a800000, v164
	v_mul_f32_e32 v95, 0x4b800000, v94
	v_cmp_gt_f32_e64 s[42:43], s9, v94
	s_nop 1
	v_cndmask_b32_e64 v94, v94, v95, s[42:43]
	v_rsq_f32_e32 v108, v94
	v_lshlrev_b64 v[94:95], 11, v[102:103]
	v_lshl_add_u64 v[94:95], v[4:5], 0, v[94:95]
	v_mul_f32_e32 v103, 0x45800000, v108
	v_cndmask_b32_e64 v108, v108, v103, s[42:43]
	v_pk_mul_f32 v[82:83], v[82:83], v[108:109] op_sel_hi:[1,0]
	v_pk_mul_f32 v[86:87], v[86:87], v[108:109] op_sel_hi:[1,0]
	v_pk_mul_f32 v[80:81], v[80:81], v[108:109] op_sel_hi:[1,0]
	v_pk_fma_f32 v[82:83], v[98:99], v[82:83], v[96:97]
	v_pk_mul_f32 v[84:85], v[84:85], v[108:109] op_sel_hi:[1,0]
	v_pk_fma_f32 v[86:87], v[100:101], v[86:87], v[16:17]
	v_pk_fma_f32 v[80:81], v[30:31], v[80:81], v[14:15]
	v_pk_fma_f32 v[84:85], v[26:27], v[84:85], v[10:11]
	v_pk_mul_f32 v[88:89], v[88:89], v[108:109] op_sel_hi:[1,0]
	v_pk_mul_f32 v[90:91], v[90:91], v[108:109] op_sel_hi:[1,0]
	v_pk_mul_f32 v[116:117], v[128:129], v[108:109] op_sel_hi:[1,0]
	v_pk_mul_f32 v[92:93], v[92:93], v[108:109] op_sel_hi:[1,0]
	v_bfe_u32 v103, v87, 16, 1
	v_bfe_u32 v108, v86, 16, 1
	v_bfe_u32 v109, v83, 16, 1
	v_bfe_u32 v115, v82, 16, 1
	v_add3_u32 v115, v82, v115, s84
	v_add3_u32 v109, v83, v109, s84
	v_add3_u32 v82, v86, v108, s84
	v_add3_u32 v83, v87, v103, s84
	v_bfe_u32 v86, v80, 16, 1
	v_bfe_u32 v87, v81, 16, 1
	v_bfe_u32 v103, v84, 16, 1
	v_bfe_u32 v108, v85, 16, 1
	v_add3_u32 v85, v85, v108, s84
	v_add3_u32 v84, v84, v103, s84
	v_add3_u32 v81, v81, v87, s84
	v_add3_u32 v80, v80, v86, s84
	v_lshrrev_b32_e32 v80, 16, v80
	v_lshrrev_b32_e32 v81, 16, v81
	v_lshrrev_b32_e32 v84, 16, v84
	v_lshrrev_b32_e32 v85, 16, v85
	v_pk_fma_f32 v[90:91], v[28:29], v[90:91], v[12:13]
	v_and_or_b32 v83, v83, s3, v85
	v_and_or_b32 v82, v82, s3, v84
	v_and_or_b32 v81, v109, s3, v81
	v_and_or_b32 v80, v115, s3, v80
	v_pk_fma_f32 v[88:89], v[22:23], v[88:89], v[6:7]
	v_pk_fma_f32 v[116:117], v[18:19], v[116:117], v[2:3]
	global_store_dwordx4 v[94:95], v[80:83], off
	v_pk_fma_f32 v[92:93], v[24:25], v[92:93], v[8:9]
	v_bfe_u32 v86, v116, 16, 1
	v_bfe_u32 v82, v91, 16, 1
	v_bfe_u32 v83, v90, 16, 1
	v_add3_u32 v84, v90, v83, s84
	v_add3_u32 v85, v91, v82, s84
	v_bfe_u32 v82, v88, 16, 1
	v_bfe_u32 v83, v89, 16, 1
	v_bfe_u32 v87, v117, 16, 1
	v_bfe_u32 v80, v93, 16, 1
	v_bfe_u32 v81, v92, 16, 1
	v_add3_u32 v87, v117, v87, s84
	v_add3_u32 v86, v116, v86, s84
	v_add3_u32 v83, v89, v83, s84
	v_add3_u32 v82, v88, v82, s84
	v_add3_u32 v81, v92, v81, s84
	v_add3_u32 v80, v93, v80, s84
	v_lshrrev_b32_e32 v88, 16, v82
	v_lshrrev_b32_e32 v89, 16, v83
	v_lshrrev_b32_e32 v82, 16, v86
	v_lshrrev_b32_e32 v83, 16, v87
	v_and_or_b32 v83, v80, s3, v83
	v_and_or_b32 v82, v81, s3, v82
	v_and_or_b32 v81, v85, s3, v89
	v_and_or_b32 v80, v84, s3, v88
	global_store_dwordx4 v[94:95], v[80:83], off offset:1024
	s_or_b64 exec, exec, s[36:37]
	s_and_saveexec_b64 s[36:37], s[40:41]
	s_cbranch_execnz .LBB0_163

; __device__ __forceinline__ void phase_ln(bf16* X, const bf16* Mx, const float* g, const float* b, int tid) {
;     ...
;         for (int u = 0; u < 4; ++u) { const int t = t0 + u * NGW; if (t < T) {
;             float x[16], m[16];
;             unpack8(xa[u][0], x); unpack8(xa[u][1], x + 8); unpack8(ma[u][0], m); unpack8(ma[u][1], m + 8);
;             float sum = 0.f;
; #pragma unroll
;             for (int i = 0; i < 16; ++i) { x[i] = ALPHA * x[i] + m[i]; sum += x[i]; }
;             const float mean = wave_sum(sum) * (1.f / DM);
;             float q = 0.f;
; #pragma unroll
;             for (int i = 0; i < 16; ++i) { x[i] -= mean; q += x[i] * x[i]; }
;             const float rstd = rsqrtf(wave_sum(q) * (1.f / DM) + LN_EPS);
.LBB0_163:
	s_waitcnt vmcnt(8)
	v_lshlrev_b32_e32 v81, 16, v45
	v_lshlrev_b32_e32 v80, 16, v44
	v_lshlrev_b32_e32 v92, 16, v68
	v_lshlrev_b32_e32 v93, 16, v69
	v_and_b32_e32 v83, 0xffff0000, v45
	v_and_b32_e32 v82, 0xffff0000, v44
	v_and_b32_e32 v94, 0xffff0000, v68
	v_and_b32_e32 v95, 0xffff0000, v69
	v_pk_fma_f32 v[80:81], v[80:81], s[14:15], v[92:93] op_sel_hi:[1,0,1]
	v_pk_fma_f32 v[82:83], v[82:83], s[14:15], v[94:95] op_sel_hi:[1,0,1]
	v_add_f32_e32 v92, 0, v80
	v_add_f32_e32 v92, v82, v92
	v_lshlrev_b32_e32 v85, 16, v47
	v_lshlrev_b32_e32 v84, 16, v46
	v_lshlrev_b32_e32 v108, 16, v70
	v_lshlrev_b32_e32 v109, 16, v71
	v_add_f32_e32 v92, v81, v92
	v_and_b32_e32 v87, 0xffff0000, v47
	v_and_b32_e32 v86, 0xffff0000, v46
	v_and_b32_e32 v116, 0xffff0000, v70
	v_and_b32_e32 v117, 0xffff0000, v71
	v_add_f32_e32 v92, v83, v92
	v_pk_fma_f32 v[84:85], v[84:85], s[14:15], v[108:109] op_sel_hi:[1,0,1]
	v_pk_fma_f32 v[86:87], v[86:87], s[14:15], v[116:117] op_sel_hi:[1,0,1]
	v_add_f32_e32 v92, v84, v92
	v_add_f32_e32 v92, v86, v92
	v_lshlrev_b32_e32 v89, 16, v41
	v_lshlrev_b32_e32 v88, 16, v40
	v_lshlrev_b32_e32 v118, 16, v64
	v_lshlrev_b32_e32 v119, 16, v65
	v_add_f32_e32 v92, v85, v92
	v_and_b32_e32 v91, 0xffff0000, v41
	v_and_b32_e32 v90, 0xffff0000, v40
	v_and_b32_e32 v120, 0xffff0000, v64
	v_and_b32_e32 v121, 0xffff0000, v65
	v_add_f32_e32 v92, v87, v92
	v_pk_fma_f32 v[88:89], v[88:89], s[14:15], v[118:119] op_sel_hi:[1,0,1]
	v_pk_fma_f32 v[90:91], v[90:91], s[14:15], v[120:121] op_sel_hi:[1,0,1]
	v_add_f32_e32 v92, v88, v92
	v_add_f32_e32 v92, v90, v92
	v_and_b32_e32 v122, 0xffff0000, v42
	v_lshlrev_b32_e32 v123, 16, v42
	v_and_b32_e32 v124, 0xffff0000, v66
	v_lshlrev_b32_e32 v125, 16, v66
	v_add_f32_e32 v92, v89, v92
	v_pk_fma_f32 v[122:123], v[122:123], s[14:15], v[124:125] op_sel_hi:[1,0,1]
	v_add_f32_e32 v92, v91, v92
	v_and_b32_e32 v124, 0xffff0000, v43
	v_lshlrev_b32_e32 v125, 16, v43
	v_and_b32_e32 v126, 0xffff0000, v67
	v_lshlrev_b32_e32 v127, 16, v67
	v_add_f32_e32 v92, v123, v92
	v_pk_fma_f32 v[124:125], v[124:125], s[14:15], v[126:127] op_sel_hi:[1,0,1]
	v_add_f32_e32 v92, v122, v92
	v_add_f32_e32 v92, v125, v92
	v_add_f32_e32 v92, v124, v92
	v_mov_b32_e32 v128, v123
	v_mov_b32_e32 v129, v125
	v_mov_b32_e32 v123, v124
	s_waitcnt lgkmcnt(0)
	s_nop 1
	v_add_f32_dpp v92, v92, v92 quad_perm:[1,0,3,2] row_mask:0xf bank_mask:0xf
	s_waitcnt lgkmcnt(0)
	s_nop 1
	v_add_f32_dpp v92, v92, v92 quad_perm:[2,3,0,1] row_mask:0xf bank_mask:0xf
	s_waitcnt lgkmcnt(0)
	s_nop 1
	v_add_f32_dpp v92, v92, v92 row_half_mirror row_mask:0xf bank_mask:0xf
	s_waitcnt lgkmcnt(0)
	s_nop 1
	v_add_f32_dpp v92, v92, v92 row_mirror row_mask:0xf bank_mask:0xf
	s_waitcnt lgkmcnt(0)
	v_mov_b32_e32 v93, v92
	s_nop 1
	v_permlane16_swap_b32_e32 v92, v93
	v_add_f32_e32 v92, v92, v93
	s_waitcnt lgkmcnt(0)
	v_mov_b32_e32 v93, v92
	s_nop 1
	v_permlane32_swap_b32_e32 v92, v93
	v_add_f32_e32 v92, v92, v93
	v_mul_f32_e32 v92, 0x3a800000, v92
	v_pk_add_f32 v[80:81], v[80:81], v[92:93] op_sel_hi:[1,0] neg_lo:[0,1] neg_hi:[0,1]
	v_pk_add_f32 v[82:83], v[82:83], v[92:93] op_sel_hi:[1,0] neg_lo:[0,1] neg_hi:[0,1]
	v_pk_mul_f32 v[94:95], v[80:81], v[80:81]
	v_pk_mul_f32 v[108:109], v[82:83], v[82:83]
	v_pk_add_f32 v[84:85], v[84:85], v[92:93] op_sel_hi:[1,0] neg_lo:[0,1] neg_hi:[0,1]
	v_add_f32_e32 v94, v94, v108
	v_add_f32_e32 v94, v95, v94
	v_pk_mul_f32 v[116:117], v[84:85], v[84:85]
	v_pk_add_f32 v[86:87], v[86:87], v[92:93] op_sel_hi:[1,0] neg_lo:[0,1] neg_hi:[0,1]
	v_add_f32_e32 v94, v109, v94
	v_pk_mul_f32 v[118:119], v[86:87], v[86:87]
	v_add_f32_e32 v94, v116, v94
	v_add_f32_e32 v94, v118, v94
	v_pk_add_f32 v[88:89], v[88:89], v[92:93] op_sel_hi:[1,0] neg_lo:[0,1] neg_hi:[0,1]
	v_add_f32_e32 v94, v117, v94
	v_pk_mul_f32 v[120:121], v[88:89], v[88:89]
	v_pk_add_f32 v[90:91], v[90:91], v[92:93] op_sel_hi:[1,0] neg_lo:[0,1] neg_hi:[0,1]
	v_add_f32_e32 v94, v119, v94
	v_pk_mul_f32 v[126:127], v[90:91], v[90:91]
	v_add_f32_e32 v94, v120, v94
	v_pk_add_f32 v[128:129], v[128:129], v[92:93] op_sel_hi:[1,0] neg_lo:[0,1] neg_hi:[0,1]
	v_pk_add_f32 v[92:93], v[122:123], v[92:93] op_sel_hi:[1,0] neg_lo:[0,1] neg_hi:[0,1]
	v_add_f32_e32 v94, v126, v94
	v_mov_b32_e32 v122, v92
	v_mov_b32_e32 v123, v128
	v_add_f32_e32 v94, v121, v94
	v_pk_mul_f32 v[122:123], v[122:123], v[122:123]
	v_add_f32_e32 v94, v127, v94
	v_mov_b32_e32 v124, v93
	v_mov_b32_e32 v125, v129
	v_add_f32_e32 v94, v123, v94
	v_pk_mul_f32 v[124:125], v[124:125], v[124:125]
	v_add_f32_e32 v94, v122, v94
	v_add_f32_e32 v94, v125, v94
	v_add_f32_e32 v94, v124, v94
	s_waitcnt lgkmcnt(0)
	s_nop 1
	v_add_f32_dpp v94, v94, v94 quad_perm:[1,0,3,2] row_mask:0xf bank_mask:0xf
	s_waitcnt lgkmcnt(0)
	s_nop 1
	v_add_f32_dpp v94, v94, v94 quad_perm:[2,3,0,1] row_mask:0xf bank_mask:0xf
	s_waitcnt lgkmcnt(0)
	s_nop 1
	v_add_f32_dpp v94, v94, v94 row_half_mirror row_mask:0xf bank_mask:0xf
	s_waitcnt lgkmcnt(0)
	s_nop 1
	v_add_f32_dpp v94, v94, v94 row_mirror row_mask:0xf bank_mask:0xf
	s_waitcnt lgkmcnt(0)
	v_mov_b32_e32 v95, v94
	s_nop 1
	v_permlane16_swap_b32_e32 v94, v95
	v_add_f32_e32 v94, v94, v95
	s_waitcnt lgkmcnt(0)
; __device__ __forceinline__ void phase_ln(bf16* X, const bf16* Mx, const float* g, const float* b, int tid) {
;     ...
;         for (int u = 0; u < 4; ++u) { const int t = t0 + u * NGW; if (t < T) {
;             float x[16], m[16];
;             unpack8(xa[u][0], x); unpack8(xa[u][1], x + 8); unpack8(ma[u][0], m); unpack8(ma[u][1], m + 8);
;             float sum = 0.f;
; #pragma unroll
;             for (int i = 0; i < 16; ++i) { x[i] = ALPHA * x[i] + m[i]; sum += x[i]; }
;             const float mean = wave_sum(sum) * (1.f / DM);
;             float q = 0.f;
; #pragma unroll
;             for (int i = 0; i < 16; ++i) { x[i] -= mean; q += x[i] * x[i]; }
;             const float rstd = rsqrtf(wave_sum(q) * (1.f / DM) + LN_EPS);
; #pragma unroll
;             for (int i = 0; i < 16; ++i) x[i] = x[i] * rstd * gg[i] + bb[i];
;             store_row_bf16(X + (size_t)t * DM, lane, x); } }
	v_mov_b32_e32 v95, v94
	s_nop 1
	v_permlane32_swap_b32_e32 v94, v95
	v_add_f32_e32 v94, v94, v95
	v_fmamk_f32 v94, v94, 0x3a800000, v164
	v_mul_f32_e32 v95, 0x4b800000, v94
	v_cmp_gt_f32_e64 s[40:41], s9, v94
	s_nop 1
	v_cndmask_b32_e64 v94, v94, v95, s[40:41]
	v_rsq_f32_e32 v103, v94
	v_lshlrev_b64 v[94:95], 11, v[106:107]
	v_lshl_add_u64 v[94:95], v[4:5], 0, v[94:95]
	v_mul_f32_e32 v106, 0x45800000, v103
	v_cndmask_b32_e64 v106, v103, v106, s[40:41]
	v_pk_mul_f32 v[82:83], v[82:83], v[106:107] op_sel_hi:[1,0]
	v_pk_mul_f32 v[86:87], v[86:87], v[106:107] op_sel_hi:[1,0]
	v_pk_mul_f32 v[80:81], v[80:81], v[106:107] op_sel_hi:[1,0]
	v_pk_fma_f32 v[82:83], v[98:99], v[82:83], v[96:97]
	v_pk_mul_f32 v[84:85], v[84:85], v[106:107] op_sel_hi:[1,0]
	v_pk_fma_f32 v[86:87], v[100:101], v[86:87], v[16:17]
	v_pk_fma_f32 v[80:81], v[30:31], v[80:81], v[14:15]
	v_pk_fma_f32 v[84:85], v[26:27], v[84:85], v[10:11]
	v_pk_mul_f32 v[88:89], v[88:89], v[106:107] op_sel_hi:[1,0]
	v_pk_mul_f32 v[90:91], v[90:91], v[106:107] op_sel_hi:[1,0]
	v_pk_mul_f32 v[108:109], v[128:129], v[106:107] op_sel_hi:[1,0]
	v_pk_mul_f32 v[92:93], v[92:93], v[106:107] op_sel_hi:[1,0]
	v_bfe_u32 v103, v87, 16, 1
	v_bfe_u32 v106, v86, 16, 1
	v_bfe_u32 v107, v83, 16, 1
	v_bfe_u32 v115, v82, 16, 1
	v_add3_u32 v115, v82, v115, s84
	v_add3_u32 v107, v83, v107, s84
	v_add3_u32 v82, v86, v106, s84
	v_add3_u32 v83, v87, v103, s84
	v_bfe_u32 v86, v80, 16, 1
	v_bfe_u32 v87, v81, 16, 1
	v_bfe_u32 v103, v84, 16, 1
	v_bfe_u32 v106, v85, 16, 1
	v_add3_u32 v85, v85, v106, s84
	v_add3_u32 v84, v84, v103, s84
	v_add3_u32 v81, v81, v87, s84
	v_add3_u32 v80, v80, v86, s84
	v_lshrrev_b32_e32 v80, 16, v80
	v_lshrrev_b32_e32 v81, 16, v81
	v_lshrrev_b32_e32 v84, 16, v84
	v_lshrrev_b32_e32 v85, 16, v85
	v_pk_fma_f32 v[90:91], v[28:29], v[90:91], v[12:13]
	v_and_or_b32 v83, v83, s3, v85
	v_and_or_b32 v82, v82, s3, v84
	v_and_or_b32 v81, v107, s3, v81
	v_and_or_b32 v80, v115, s3, v80
	v_pk_fma_f32 v[88:89], v[22:23], v[88:89], v[6:7]
	v_pk_fma_f32 v[108:109], v[18:19], v[108:109], v[2:3]
	global_store_dwordx4 v[94:95], v[80:83], off
	v_pk_fma_f32 v[92:93], v[24:25], v[92:93], v[8:9]
	v_bfe_u32 v86, v108, 16, 1
	v_bfe_u32 v82, v91, 16, 1
	v_bfe_u32 v83, v90, 16, 1
	v_add3_u32 v84, v90, v83, s84
	v_add3_u32 v85, v91, v82, s84
	v_bfe_u32 v82, v88, 16, 1
	v_bfe_u32 v83, v89, 16, 1
	v_bfe_u32 v87, v109, 16, 1
	v_bfe_u32 v80, v93, 16, 1
	v_bfe_u32 v81, v92, 16, 1
	v_add3_u32 v87, v109, v87, s84
	v_add3_u32 v86, v108, v86, s84
	v_add3_u32 v83, v89, v83, s84
	v_add3_u32 v82, v88, v82, s84
	v_add3_u32 v81, v92, v81, s84
	v_add3_u32 v80, v93, v80, s84
	v_lshrrev_b32_e32 v88, 16, v82
	v_lshrrev_b32_e32 v89, 16, v83
	v_lshrrev_b32_e32 v82, 16, v86
	v_lshrrev_b32_e32 v83, 16, v87
	v_and_or_b32 v83, v80, s3, v83
	v_and_or_b32 v82, v81, s3, v82
	v_and_or_b32 v81, v85, s3, v89
	v_and_or_b32 v80, v84, s3, v88
	global_store_dwordx4 v[94:95], v[80:83], off offset:1024
	s_or_b64 exec, exec, s[36:37]
	s_and_saveexec_b64 s[36:37], vcc
	s_cbranch_execz .LBB0_152
.LBB0_164:
	s_waitcnt vmcnt(6)
	v_lshlrev_b32_e32 v81, 16, v37
	v_lshlrev_b32_e32 v80, 16, v36
	v_lshlrev_b32_e32 v92, 16, v60
	v_lshlrev_b32_e32 v93, 16, v61
	v_and_b32_e32 v83, 0xffff0000, v37
	v_and_b32_e32 v82, 0xffff0000, v36
	v_and_b32_e32 v94, 0xffff0000, v60
	v_and_b32_e32 v95, 0xffff0000, v61
	v_pk_fma_f32 v[80:81], v[80:81], s[14:15], v[92:93] op_sel_hi:[1,0,1]
	v_pk_fma_f32 v[82:83], v[82:83], s[14:15], v[94:95] op_sel_hi:[1,0,1]
	v_add_f32_e32 v92, 0, v80
	v_add_f32_e32 v92, v82, v92
	v_lshlrev_b32_e32 v85, 16, v39
	v_lshlrev_b32_e32 v84, 16, v38
	v_lshlrev_b32_e32 v106, 16, v62
	v_lshlrev_b32_e32 v107, 16, v63
	v_add_f32_e32 v92, v81, v92
	v_and_b32_e32 v87, 0xffff0000, v39
	v_and_b32_e32 v86, 0xffff0000, v38
	v_and_b32_e32 v108, 0xffff0000, v62
	v_and_b32_e32 v109, 0xffff0000, v63
	v_add_f32_e32 v92, v83, v92
	v_pk_fma_f32 v[84:85], v[84:85], s[14:15], v[106:107] op_sel_hi:[1,0,1]
	v_pk_fma_f32 v[86:87], v[86:87], s[14:15], v[108:109] op_sel_hi:[1,0,1]
	v_add_f32_e32 v92, v84, v92
	v_add_f32_e32 v92, v86, v92
	v_lshlrev_b32_e32 v89, 16, v33
	v_lshlrev_b32_e32 v88, 16, v32
	v_lshlrev_b32_e32 v116, 16, v56
	v_lshlrev_b32_e32 v117, 16, v57
	v_add_f32_e32 v92, v85, v92
	v_and_b32_e32 v91, 0xffff0000, v33
	v_and_b32_e32 v90, 0xffff0000, v32
	v_and_b32_e32 v118, 0xffff0000, v56
	v_and_b32_e32 v119, 0xffff0000, v57
	v_add_f32_e32 v92, v87, v92
	v_pk_fma_f32 v[88:89], v[88:89], s[14:15], v[116:117] op_sel_hi:[1,0,1]
	v_pk_fma_f32 v[90:91], v[90:91], s[14:15], v[118:119] op_sel_hi:[1,0,1]
	v_add_f32_e32 v92, v88, v92
	v_add_f32_e32 v92, v90, v92
	v_and_b32_e32 v120, 0xffff0000, v34
	v_lshlrev_b32_e32 v121, 16, v34
	v_and_b32_e32 v122, 0xffff0000, v58
	v_lshlrev_b32_e32 v123, 16, v58
	v_add_f32_e32 v92, v89, v92
	v_pk_fma_f32 v[120:121], v[120:121], s[14:15], v[122:123] op_sel_hi:[1,0,1]
	v_add_f32_e32 v92, v91, v92
	v_and_b32_e32 v122, 0xffff0000, v35
	v_lshlrev_b32_e32 v123, 16, v35
	v_and_b32_e32 v124, 0xffff0000, v59
	v_lshlrev_b32_e32 v125, 16, v59
	v_add_f32_e32 v92, v121, v92
	v_pk_fma_f32 v[122:123], v[122:123], s[14:15], v[124:125] op_sel_hi:[1,0,1]
	v_add_f32_e32 v92, v120, v92
	v_add_f32_e32 v92, v123, v92
	v_add_f32_e32 v92, v122, v92
	v_mov_b32_e32 v126, v121
	v_mov_b32_e32 v127, v123
	v_mov_b32_e32 v121, v122
	s_waitcnt lgkmcnt(0)
	s_nop 1
	v_add_f32_dpp v92, v92, v92 quad_perm:[1,0,3,2] row_mask:0xf bank_mask:0xf
	s_waitcnt lgkmcnt(0)
	s_nop 1
	v_add_f32_dpp v92, v92, v92 quad_perm:[2,3,0,1] row_mask:0xf bank_mask:0xf
	s_waitcnt lgkmcnt(0)
; __device__ __forceinline__ void phase_ln(bf16* X, const bf16* Mx, const float* g, const float* b, int tid) {
;     ...
;             const float mean = wave_sum(sum) * (1.f / DM);
;             float q = 0.f;
; #pragma unroll
;             for (int i = 0; i < 16; ++i) { x[i] -= mean; q += x[i] * x[i]; }
;             const float rstd = rsqrtf(wave_sum(q) * (1.f / DM) + LN_EPS);
; #pragma unroll
;             for (int i = 0; i < 16; ++i) x[i] = x[i] * rstd * gg[i] + bb[i];
;             store_row_bf16(X + (size_t)t * DM, lane, x); } }
	s_nop 1
	v_add_f32_dpp v92, v92, v92 row_half_mirror row_mask:0xf bank_mask:0xf
	s_waitcnt lgkmcnt(0)
	s_nop 1
	v_add_f32_dpp v92, v92, v92 row_mirror row_mask:0xf bank_mask:0xf
	s_waitcnt lgkmcnt(0)
	v_mov_b32_e32 v93, v92
	s_nop 1
	v_permlane16_swap_b32_e32 v92, v93
	v_add_f32_e32 v92, v92, v93
	s_waitcnt lgkmcnt(0)
	v_mov_b32_e32 v93, v92
	s_nop 1
	v_permlane32_swap_b32_e32 v92, v93
	v_add_f32_e32 v92, v92, v93
	v_mul_f32_e32 v92, 0x3a800000, v92
	v_pk_add_f32 v[80:81], v[80:81], v[92:93] op_sel_hi:[1,0] neg_lo:[0,1] neg_hi:[0,1]
	v_pk_add_f32 v[82:83], v[82:83], v[92:93] op_sel_hi:[1,0] neg_lo:[0,1] neg_hi:[0,1]
	v_pk_mul_f32 v[94:95], v[80:81], v[80:81]
	v_pk_mul_f32 v[106:107], v[82:83], v[82:83]
	v_pk_add_f32 v[84:85], v[84:85], v[92:93] op_sel_hi:[1,0] neg_lo:[0,1] neg_hi:[0,1]
	v_add_f32_e32 v94, v94, v106
	v_add_f32_e32 v94, v95, v94
	v_pk_mul_f32 v[108:109], v[84:85], v[84:85]
	v_pk_add_f32 v[86:87], v[86:87], v[92:93] op_sel_hi:[1,0] neg_lo:[0,1] neg_hi:[0,1]
	v_add_f32_e32 v94, v107, v94
	v_pk_mul_f32 v[116:117], v[86:87], v[86:87]
	v_add_f32_e32 v94, v108, v94
	v_add_f32_e32 v94, v116, v94
	v_pk_add_f32 v[88:89], v[88:89], v[92:93] op_sel_hi:[1,0] neg_lo:[0,1] neg_hi:[0,1]
	v_add_f32_e32 v94, v109, v94
	v_pk_mul_f32 v[118:119], v[88:89], v[88:89]
	v_pk_add_f32 v[90:91], v[90:91], v[92:93] op_sel_hi:[1,0] neg_lo:[0,1] neg_hi:[0,1]
	v_add_f32_e32 v94, v117, v94
	v_pk_mul_f32 v[124:125], v[90:91], v[90:91]
	v_add_f32_e32 v94, v118, v94
	v_pk_add_f32 v[126:127], v[126:127], v[92:93] op_sel_hi:[1,0] neg_lo:[0,1] neg_hi:[0,1]
	v_pk_add_f32 v[92:93], v[120:121], v[92:93] op_sel_hi:[1,0] neg_lo:[0,1] neg_hi:[0,1]
	v_add_f32_e32 v94, v124, v94
	v_mov_b32_e32 v120, v92
	v_mov_b32_e32 v121, v126
	v_add_f32_e32 v94, v119, v94
	v_pk_mul_f32 v[120:121], v[120:121], v[120:121]
	v_add_f32_e32 v94, v125, v94
	v_mov_b32_e32 v122, v93
	v_mov_b32_e32 v123, v127
	v_add_f32_e32 v94, v121, v94
	v_pk_mul_f32 v[122:123], v[122:123], v[122:123]
	v_add_f32_e32 v94, v120, v94
	v_add_f32_e32 v94, v123, v94
	v_add_f32_e32 v94, v122, v94
	s_waitcnt lgkmcnt(0)
	s_nop 1
	v_add_f32_dpp v94, v94, v94 quad_perm:[1,0,3,2] row_mask:0xf bank_mask:0xf
	s_waitcnt lgkmcnt(0)
	s_nop 1
	v_add_f32_dpp v94, v94, v94 quad_perm:[2,3,0,1] row_mask:0xf bank_mask:0xf
	s_waitcnt lgkmcnt(0)
	s_nop 1
	v_add_f32_dpp v94, v94, v94 row_half_mirror row_mask:0xf bank_mask:0xf
	s_waitcnt lgkmcnt(0)
	s_nop 1
	v_add_f32_dpp v94, v94, v94 row_mirror row_mask:0xf bank_mask:0xf
	s_waitcnt lgkmcnt(0)
	v_mov_b32_e32 v95, v94
	s_nop 1
	v_permlane16_swap_b32_e32 v94, v95
	v_add_f32_e32 v94, v94, v95
	s_waitcnt lgkmcnt(0)
	v_mov_b32_e32 v95, v94
	s_nop 1
	v_permlane32_swap_b32_e32 v94, v95
	v_add_f32_e32 v94, v94, v95
	v_fmamk_f32 v94, v94, 0x3a800000, v164
	v_mul_f32_e32 v95, 0x4b800000, v94
	v_cmp_gt_f32_e32 vcc, s9, v94
	s_nop 1
	v_cndmask_b32_e32 v94, v94, v95, vcc
	v_rsq_f32_e32 v103, v94
	v_lshlrev_b64 v[94:95], 11, v[104:105]
	v_lshl_add_u64 v[94:95], v[4:5], 0, v[94:95]
	v_mul_f32_e32 v104, 0x45800000, v103
	v_cndmask_b32_e32 v104, v103, v104, vcc
	v_pk_mul_f32 v[82:83], v[82:83], v[104:105] op_sel_hi:[1,0]
	v_pk_mul_f32 v[86:87], v[86:87], v[104:105] op_sel_hi:[1,0]
	v_pk_mul_f32 v[80:81], v[80:81], v[104:105] op_sel_hi:[1,0]
	v_pk_fma_f32 v[82:83], v[98:99], v[82:83], v[96:97]
	v_pk_mul_f32 v[84:85], v[84:85], v[104:105] op_sel_hi:[1,0]
	v_pk_fma_f32 v[86:87], v[100:101], v[86:87], v[16:17]
	v_pk_fma_f32 v[80:81], v[30:31], v[80:81], v[14:15]
	v_pk_fma_f32 v[84:85], v[26:27], v[84:85], v[10:11]
	v_pk_mul_f32 v[88:89], v[88:89], v[104:105] op_sel_hi:[1,0]
	v_pk_mul_f32 v[90:91], v[90:91], v[104:105] op_sel_hi:[1,0]
	v_pk_mul_f32 v[106:107], v[126:127], v[104:105] op_sel_hi:[1,0]
	v_pk_mul_f32 v[92:93], v[92:93], v[104:105] op_sel_hi:[1,0]
	v_bfe_u32 v103, v87, 16, 1
	v_bfe_u32 v104, v86, 16, 1
	v_bfe_u32 v105, v83, 16, 1
	v_bfe_u32 v108, v82, 16, 1
	v_add3_u32 v108, v82, v108, s84
	v_add3_u32 v105, v83, v105, s84
	v_add3_u32 v82, v86, v104, s84
	v_add3_u32 v83, v87, v103, s84
	v_bfe_u32 v86, v80, 16, 1
	v_bfe_u32 v87, v81, 16, 1
	v_bfe_u32 v103, v84, 16, 1
	v_bfe_u32 v104, v85, 16, 1
	v_add3_u32 v85, v85, v104, s84
	v_add3_u32 v84, v84, v103, s84
	v_add3_u32 v81, v81, v87, s84
	v_add3_u32 v80, v80, v86, s84
	v_lshrrev_b32_e32 v80, 16, v80
	v_lshrrev_b32_e32 v81, 16, v81
	v_lshrrev_b32_e32 v84, 16, v84
	v_lshrrev_b32_e32 v85, 16, v85
	v_pk_fma_f32 v[90:91], v[28:29], v[90:91], v[12:13]
	v_and_or_b32 v83, v83, s3, v85
	v_and_or_b32 v82, v82, s3, v84
	v_and_or_b32 v81, v105, s3, v81
	v_and_or_b32 v80, v108, s3, v80
	v_pk_fma_f32 v[88:89], v[22:23], v[88:89], v[6:7]
	v_pk_fma_f32 v[106:107], v[18:19], v[106:107], v[2:3]
	global_store_dwordx4 v[94:95], v[80:83], off
	v_pk_fma_f32 v[92:93], v[24:25], v[92:93], v[8:9]
	v_bfe_u32 v86, v106, 16, 1
	v_bfe_u32 v82, v91, 16, 1
	v_bfe_u32 v83, v90, 16, 1
	v_add3_u32 v84, v90, v83, s84
	v_add3_u32 v85, v91, v82, s84
	v_bfe_u32 v82, v88, 16, 1
	v_bfe_u32 v83, v89, 16, 1
	v_bfe_u32 v87, v107, 16, 1
	v_bfe_u32 v80, v93, 16, 1
	v_bfe_u32 v81, v92, 16, 1
	v_add3_u32 v87, v107, v87, s84
	v_add3_u32 v86, v106, v86, s84
	v_add3_u32 v83, v89, v83, s84
	v_add3_u32 v82, v88, v82, s84
	v_add3_u32 v81, v92, v81, s84
	v_add3_u32 v80, v93, v80, s84
	v_lshrrev_b32_e32 v88, 16, v82
	v_lshrrev_b32_e32 v89, 16, v83
	v_lshrrev_b32_e32 v82, 16, v86
	v_lshrrev_b32_e32 v83, 16, v87
	v_and_or_b32 v83, v80, s3, v83
	v_and_or_b32 v82, v81, s3, v82
	v_and_or_b32 v81, v85, s3, v89
	v_and_or_b32 v80, v84, s3, v88
	global_store_dwordx4 v[94:95], v[80:83], off offset:1024
	s_branch .LBB0_152

; __device__ __forceinline__ u32x4 pack8(const float* f) { u32x4 o; o.x = pk2(f[0], f[1]); o.y = pk2(f[2], f[3]); o.z = pk2(f[4], f[5]); o.w = pk2(f[6], f[7]); return o; }
; __device__ __forceinline__ void phase_norm(bf16* Y, const float* g, int tid) {
;     ...
;         for (int u = 0; u < 4; ++u) { const int t = t0 + u * NGW; if (t < T) {
;             bf16* row = Y + (size_t)t * DM + lane * 16;
;             float y[16];
;             unpack8(ya[u][0], y); unpack8(ya[u][1], y + 8);
;             float ss = 0.f;
; #pragma unroll
;             for (int i = 0; i < 16; ++i) ss += y[i] * y[i];
;             ss += __shfl_xor(ss, 1); ss += __shfl_xor(ss, 2); ss += __shfl_xor(ss, 4); ss += __shfl_xor(ss, 8);
;             const float r = rsqrtf(ss * (1.f / 256.f) + 1e-6f);
; #pragma unroll
;             for (int i = 0; i < 16; ++i) y[i] = y[i] * r * gg[i];
;             *(u32x4*)row = pack8(y); *(u32x4*)(row + 8) = pack8(y + 8); } }
.Lnm_fast:
	s_waitcnt vmcnt(6)
	v_lshlrev_b32_e32 v71, 16, v45
	v_lshlrev_b32_e32 v70, 16, v44
	v_and_b32_e32 v45, 0xffff0000, v45
	v_and_b32_e32 v44, 0xffff0000, v44
	v_pk_mul_f32 v[72:73], v[70:71], v[70:71]
	v_pk_mul_f32 v[74:75], v[44:45], v[44:45]
	v_lshlrev_b32_e32 v77, 16, v47
	v_add_f32_e32 v63, v72, v74
	v_lshlrev_b32_e32 v76, 16, v46
	v_add_f32_e32 v63, v73, v63
	v_and_b32_e32 v47, 0xffff0000, v47
	v_and_b32_e32 v46, 0xffff0000, v46
	v_pk_mul_f32 v[78:79], v[76:77], v[76:77]
	v_add_f32_e32 v63, v75, v63
	v_pk_mul_f32 v[80:81], v[46:47], v[46:47]
	v_add_f32_e32 v63, v78, v63
	v_add_f32_e32 v63, v80, v63
	v_add_f32_e32 v63, v79, v63
	v_lshlrev_b32_e32 v83, 16, v41
	v_lshlrev_b32_e32 v82, 16, v40
	v_and_b32_e32 v41, 0xffff0000, v41
	v_add_f32_e32 v63, v81, v63
	v_and_b32_e32 v40, 0xffff0000, v40
	v_mov_b32_e32 v84, v41
	v_mov_b32_e32 v85, v83
	v_fmac_f32_e32 v63, v82, v82
	v_pk_mul_f32 v[84:85], v[84:85], v[84:85]
	v_fmac_f32_e32 v63, v40, v40
	v_and_b32_e32 v64, 0xffff0000, v42
	v_lshlrev_b32_e32 v65, 16, v42
	v_add_f32_e32 v63, v85, v63
	v_pk_mul_f32 v[66:67], v[64:65], v[64:65]
	v_add_f32_e32 v63, v84, v63
	v_and_b32_e32 v68, 0xffff0000, v43
	v_lshlrev_b32_e32 v69, 16, v43
	v_add_f32_e32 v63, v67, v63
	v_pk_mul_f32 v[42:43], v[68:69], v[68:69]
	v_add_f32_e32 v63, v66, v63
	v_add_f32_e32 v43, v43, v63
	v_add_f32_e32 v42, v42, v43
	s_mov_b32 s9, 0x800000
	s_waitcnt lgkmcnt(0)
	s_nop 1
	v_add_f32_dpp v42, v42, v42 quad_perm:[1,0,3,2] row_mask:0xf bank_mask:0xf
	s_waitcnt lgkmcnt(0)
	s_nop 1
	v_add_f32_dpp v42, v42, v42 quad_perm:[2,3,0,1] row_mask:0xf bank_mask:0xf
	s_waitcnt lgkmcnt(0)
	s_nop 1
	v_add_f32_dpp v42, v42, v42 row_half_mirror row_mask:0xf bank_mask:0xf
	s_waitcnt lgkmcnt(0)
	s_nop 1
	v_add_f32_dpp v42, v42, v42 row_mirror row_mask:0xf bank_mask:0xf
	v_fmamk_f32 v42, v42, 0x3b800000, v165
	v_mul_f32_e32 v43, 0x4b800000, v42
	v_cmp_gt_f32_e64 s[44:45], s9, v42
	s_nop 1
	v_cndmask_b32_e64 v42, v42, v43, s[44:45]
	v_rsq_f32_e32 v42, v42
	s_nop 0
	v_mul_f32_e32 v43, 0x45800000, v42
	v_cndmask_b32_e64 v66, v42, v43, s[44:45]
	v_pk_mul_f32 v[44:45], v[66:67], v[44:45] op_sel_hi:[0,1]
	v_pk_mul_f32 v[46:47], v[66:67], v[46:47] op_sel_hi:[0,1]
	v_pk_mul_f32 v[42:43], v[66:67], v[70:71] op_sel_hi:[0,1]
	v_pk_mul_f32 v[44:45], v[50:51], v[44:45]
	v_pk_mul_f32 v[70:71], v[66:67], v[76:77] op_sel_hi:[0,1]
	v_pk_mul_f32 v[46:47], v[4:5], v[46:47]
	v_pk_mul_f32 v[40:41], v[66:67], v[40:41] op_sel_hi:[0,1]
	v_pk_mul_f32 v[42:43], v[2:3], v[42:43]
	v_pk_mul_f32 v[70:71], v[6:7], v[70:71]
	v_pk_mul_f32 v[72:73], v[66:67], v[82:83] op_sel_hi:[0,1]
	v_pk_mul_f32 v[74:75], v[8:9], v[40:41]
	v_bfe_u32 v40, v47, 16, 1
	v_bfe_u32 v41, v46, 16, 1
	v_bfe_u32 v63, v45, 16, 1
	v_bfe_u32 v67, v44, 16, 1
	v_add3_u32 v44, v44, v67, s84
	v_add3_u32 v45, v45, v63, s84
	v_add3_u32 v41, v46, v41, s84
	v_add3_u32 v40, v47, v40, s84
	v_bfe_u32 v46, v42, 16, 1
	v_bfe_u32 v47, v43, 16, 1
	v_bfe_u32 v63, v70, 16, 1
	v_bfe_u32 v67, v71, 16, 1
	v_add3_u32 v67, v71, v67, s84
	v_add3_u32 v63, v70, v63, s84
	v_add3_u32 v43, v43, v47, s84
	v_add3_u32 v42, v42, v46, s84
	v_lshrrev_b32_e32 v46, 16, v42
	v_lshrrev_b32_e32 v47, 16, v43
	v_lshrrev_b32_e32 v42, 16, v63
	v_lshrrev_b32_e32 v43, 16, v67
	v_and_or_b32 v43, v40, s3, v43
	v_and_or_b32 v42, v41, s3, v42
	v_and_or_b32 v41, v45, s3, v47
	v_and_or_b32 v40, v44, s3, v46
	global_store_dwordx4 v[58:59], v[40:43], off
	v_pk_mul_f32 v[72:73], v[10:11], v[72:73]
	v_bfe_u32 v46, v75, 16, 1
	v_mov_b32_e32 v40, v65
	v_mov_b32_e32 v65, v68
	v_mov_b32_e32 v41, v69
	v_pk_mul_f32 v[42:43], v[66:67], v[64:65] op_sel_hi:[0,1]
	v_pk_mul_f32 v[40:41], v[66:67], v[40:41] op_sel_hi:[0,1]
	v_pk_mul_f32 v[42:43], v[12:13], v[42:43]
	v_pk_mul_f32 v[40:41], v[14:15], v[40:41]
	v_bfe_u32 v44, v43, 16, 1
	v_bfe_u32 v45, v42, 16, 1
	v_add3_u32 v42, v42, v45, s84
	v_add3_u32 v43, v43, v44, s84
	v_bfe_u32 v44, v72, 16, 1
	v_bfe_u32 v45, v73, 16, 1
	v_bfe_u32 v63, v40, 16, 1
	v_bfe_u32 v64, v41, 16, 1
	v_bfe_u32 v47, v74, 16, 1
	v_add3_u32 v41, v41, v64, s84
	v_add3_u32 v40, v40, v63, s84
	v_add3_u32 v45, v73, v45, s84
	v_add3_u32 v44, v72, v44, s84
	v_add3_u32 v47, v74, v47, s84
	v_add3_u32 v46, v75, v46, s84
	v_lshrrev_b32_e32 v44, 16, v44
	v_lshrrev_b32_e32 v45, 16, v45
	v_lshrrev_b32_e32 v40, 16, v40
	v_lshrrev_b32_e32 v41, 16, v41
	v_and_or_b32 v43, v43, s3, v41
	v_and_or_b32 v42, v42, s3, v40
	v_and_or_b32 v41, v46, s3, v45
	v_and_or_b32 v40, v47, s3, v44
	global_store_dwordx4 v[58:59], v[40:43], off offset:16
	s_and_saveexec_b64 s[36:37], s[42:43]
	s_cbranch_execz .LBB0_179
; __device__ __forceinline__ u32x4 pack8(const float* f) { u32x4 o; o.x = pk2(f[0], f[1]); o.y = pk2(f[2], f[3]); o.z = pk2(f[4], f[5]); o.w = pk2(f[6], f[7]); return o; }
; __device__ __forceinline__ void phase_norm(bf16* Y, const float* g, int tid) {
;     ...
;         for (int u = 0; u < 4; ++u) { const int t = t0 + u * NGW; if (t < T) {
;             bf16* row = Y + (size_t)t * DM + lane * 16;
;             float y[16];
;             unpack8(ya[u][0], y); unpack8(ya[u][1], y + 8);
;             float ss = 0.f;
; #pragma unroll
;             for (int i = 0; i < 16; ++i) ss += y[i] * y[i];
;             ss += __shfl_xor(ss, 1); ss += __shfl_xor(ss, 2); ss += __shfl_xor(ss, 4); ss += __shfl_xor(ss, 8);
;             const float r = rsqrtf(ss * (1.f / 256.f) + 1e-6f);
; #pragma unroll
;             for (int i = 0; i < 16; ++i) y[i] = y[i] * r * gg[i];
;             *(u32x4*)row = pack8(y); *(u32x4*)(row + 8) = pack8(y + 8); } }
	s_waitcnt vmcnt(6)
	v_lshlrev_b32_e32 v59, 16, v37
	v_lshlrev_b32_e32 v58, 16, v36
	v_and_b32_e32 v65, 0xffff0000, v37
	v_and_b32_e32 v64, 0xffff0000, v36
	v_pk_mul_f32 v[66:67], v[58:59], v[58:59]
	v_pk_mul_f32 v[68:69], v[64:65], v[64:65]
	v_lshlrev_b32_e32 v71, 16, v39
	v_add_f32_e32 v63, v66, v68
	v_lshlrev_b32_e32 v70, 16, v38
	v_add_f32_e32 v63, v67, v63
	v_and_b32_e32 v73, 0xffff0000, v39
	v_and_b32_e32 v72, 0xffff0000, v38
	v_pk_mul_f32 v[74:75], v[70:71], v[70:71]
	v_add_f32_e32 v63, v69, v63
	v_pk_mul_f32 v[76:77], v[72:73], v[72:73]
	v_add_f32_e32 v63, v74, v63
	v_add_f32_e32 v63, v76, v63
	v_add_f32_e32 v63, v75, v63
	v_lshlrev_b32_e32 v79, 16, v29
	v_lshlrev_b32_e32 v78, 16, v28
	v_and_b32_e32 v81, 0xffff0000, v29
	v_add_f32_e32 v63, v77, v63
	v_and_b32_e32 v80, 0xffff0000, v28
	v_mov_b32_e32 v82, v81
	v_mov_b32_e32 v83, v79
	v_fmac_f32_e32 v63, v78, v78
	v_pk_mul_f32 v[82:83], v[82:83], v[82:83]
	v_fmac_f32_e32 v63, v80, v80
	v_and_b32_e32 v44, 0xffff0000, v30
	v_lshlrev_b32_e32 v45, 16, v30
	v_add_f32_e32 v63, v83, v63
	v_pk_mul_f32 v[40:41], v[44:45], v[44:45]
	v_add_f32_e32 v63, v82, v63
	v_and_b32_e32 v46, 0xffff0000, v31
	v_lshlrev_b32_e32 v47, 16, v31
	v_add_f32_e32 v41, v41, v63
	v_pk_mul_f32 v[42:43], v[46:47], v[46:47]
	v_add_f32_e32 v40, v40, v41
	v_add_f32_e32 v40, v43, v40
	v_add_f32_e32 v40, v42, v40
	s_waitcnt lgkmcnt(0)
	s_nop 1
	v_add_f32_dpp v40, v40, v40 quad_perm:[1,0,3,2] row_mask:0xf bank_mask:0xf
	s_waitcnt lgkmcnt(0)
	s_nop 1
	v_add_f32_dpp v40, v40, v40 quad_perm:[2,3,0,1] row_mask:0xf bank_mask:0xf
	s_waitcnt lgkmcnt(0)
	s_nop 1
	v_add_f32_dpp v40, v40, v40 row_half_mirror row_mask:0xf bank_mask:0xf
	s_waitcnt lgkmcnt(0)
	s_nop 1
	v_add_f32_dpp v40, v40, v40 row_mirror row_mask:0xf bank_mask:0xf
	v_fmamk_f32 v40, v40, 0x3b800000, v165
	v_mul_f32_e32 v41, 0x4b800000, v40
	v_cmp_gt_f32_e64 s[42:43], s9, v40
	s_nop 1
	v_cndmask_b32_e64 v40, v40, v41, s[42:43]
	v_rsq_f32_e32 v42, v40
	v_lshlrev_b64 v[40:41], 11, v[52:53]
	v_lshl_add_u64 v[66:67], v[48:49], 0, v[40:41]
	v_mul_f32_e32 v40, 0x45800000, v42
	v_cndmask_b32_e64 v68, v42, v40, s[42:43]
	v_pk_mul_f32 v[42:43], v[68:69], v[64:65] op_sel_hi:[0,1]
	v_pk_mul_f32 v[64:65], v[68:69], v[72:73] op_sel_hi:[0,1]
	v_pk_mul_f32 v[40:41], v[68:69], v[58:59] op_sel_hi:[0,1]
	v_pk_mul_f32 v[42:43], v[50:51], v[42:43]
	v_pk_mul_f32 v[58:59], v[68:69], v[70:71] op_sel_hi:[0,1]
	v_pk_mul_f32 v[64:65], v[4:5], v[64:65]
	v_pk_mul_f32 v[40:41], v[2:3], v[40:41]
	v_pk_mul_f32 v[58:59], v[6:7], v[58:59]
	v_pk_mul_f32 v[70:71], v[68:69], v[78:79] op_sel_hi:[0,1]
	v_pk_mul_f32 v[72:73], v[68:69], v[80:81] op_sel_hi:[0,1]
	v_bfe_u32 v53, v65, 16, 1
	v_bfe_u32 v63, v64, 16, 1
	v_bfe_u32 v69, v43, 16, 1
	v_bfe_u32 v74, v42, 16, 1
	v_add3_u32 v74, v42, v74, s84
	v_add3_u32 v69, v43, v69, s84
	v_add3_u32 v42, v64, v63, s84
	v_add3_u32 v43, v65, v53, s84
	v_bfe_u32 v53, v40, 16, 1
	v_bfe_u32 v63, v41, 16, 1
	v_bfe_u32 v64, v58, 16, 1
	v_bfe_u32 v65, v59, 16, 1
	v_add3_u32 v59, v59, v65, s84
	v_add3_u32 v58, v58, v64, s84
	v_add3_u32 v41, v41, v63, s84
	v_add3_u32 v40, v40, v53, s84
	v_lshrrev_b32_e32 v40, 16, v40
	v_lshrrev_b32_e32 v41, 16, v41
	v_lshrrev_b32_e32 v53, 16, v58
	v_lshrrev_b32_e32 v58, 16, v59
	v_and_or_b32 v43, v43, s3, v58
	v_and_or_b32 v42, v42, s3, v53
	v_and_or_b32 v41, v69, s3, v41
	v_and_or_b32 v40, v74, s3, v40
	global_store_dwordx4 v[66:67], v[40:43], off
	v_pk_mul_f32 v[70:71], v[10:11], v[70:71]
	v_pk_mul_f32 v[72:73], v[8:9], v[72:73]
	v_mov_b32_e32 v40, v45
	v_mov_b32_e32 v45, v46
	v_mov_b32_e32 v41, v47
	v_pk_mul_f32 v[42:43], v[68:69], v[44:45] op_sel_hi:[0,1]
	v_pk_mul_f32 v[40:41], v[68:69], v[40:41] op_sel_hi:[0,1]
	v_pk_mul_f32 v[42:43], v[12:13], v[42:43]
	v_pk_mul_f32 v[40:41], v[14:15], v[40:41]
	v_bfe_u32 v44, v43, 16, 1
	v_bfe_u32 v45, v42, 16, 1
	v_add3_u32 v42, v42, v45, s84
	v_add3_u32 v43, v43, v44, s84
	v_bfe_u32 v44, v70, 16, 1
	v_bfe_u32 v45, v71, 16, 1
	v_bfe_u32 v53, v40, 16, 1
	v_bfe_u32 v58, v41, 16, 1
	v_bfe_u32 v46, v73, 16, 1
	v_bfe_u32 v47, v72, 16, 1
	v_add3_u32 v41, v41, v58, s84
	v_add3_u32 v40, v40, v53, s84
	v_add3_u32 v45, v71, v45, s84
	v_add3_u32 v44, v70, v44, s84
	v_add3_u32 v47, v72, v47, s84
	v_add3_u32 v46, v73, v46, s84
	v_lshrrev_b32_e32 v44, 16, v44
	v_lshrrev_b32_e32 v45, 16, v45
	v_lshrrev_b32_e32 v40, 16, v40
	v_lshrrev_b32_e32 v41, 16, v41
	v_and_or_b32 v43, v43, s3, v41
	v_and_or_b32 v42, v42, s3, v40
	v_and_or_b32 v41, v46, s3, v45
	v_and_or_b32 v40, v47, s3, v44
	global_store_dwordx4 v[66:67], v[40:43], off offset:16
	s_or_b64 exec, exec, s[36:37]
	s_and_saveexec_b64 s[36:37], s[40:41]
	s_cbranch_execnz .LBB0_180

; __device__ __forceinline__ u32x4 pack8(const float* f) { u32x4 o; o.x = pk2(f[0], f[1]); o.y = pk2(f[2], f[3]); o.z = pk2(f[4], f[5]); o.w = pk2(f[6], f[7]); return o; }
; __device__ __forceinline__ void phase_norm(bf16* Y, const float* g, int tid) {
;     ...
;         for (int u = 0; u < 4; ++u) { const int t = t0 + u * NGW; if (t < T) {
;             bf16* row = Y + (size_t)t * DM + lane * 16;
;             float y[16];
;             unpack8(ya[u][0], y); unpack8(ya[u][1], y + 8);
;             float ss = 0.f;
; #pragma unroll
;             for (int i = 0; i < 16; ++i) ss += y[i] * y[i];
;             ss += __shfl_xor(ss, 1); ss += __shfl_xor(ss, 2); ss += __shfl_xor(ss, 4); ss += __shfl_xor(ss, 8);
;             const float r = rsqrtf(ss * (1.f / 256.f) + 1e-6f);
; #pragma unroll
;             for (int i = 0; i < 16; ++i) y[i] = y[i] * r * gg[i];
;             *(u32x4*)row = pack8(y); *(u32x4*)(row + 8) = pack8(y + 8); } }
.LBB0_180:
	s_waitcnt vmcnt(6)
	v_lshlrev_b32_e32 v59, 16, v33
	v_lshlrev_b32_e32 v58, 16, v32
	v_and_b32_e32 v65, 0xffff0000, v33
	v_and_b32_e32 v64, 0xffff0000, v32
	v_pk_mul_f32 v[66:67], v[58:59], v[58:59]
	v_pk_mul_f32 v[68:69], v[64:65], v[64:65]
	v_lshlrev_b32_e32 v71, 16, v35
	v_add_f32_e32 v53, v66, v68
	v_lshlrev_b32_e32 v70, 16, v34
	v_add_f32_e32 v53, v67, v53
	v_and_b32_e32 v73, 0xffff0000, v35
	v_and_b32_e32 v72, 0xffff0000, v34
	v_pk_mul_f32 v[74:75], v[70:71], v[70:71]
	v_add_f32_e32 v53, v69, v53
	v_pk_mul_f32 v[76:77], v[72:73], v[72:73]
	v_add_f32_e32 v53, v74, v53
	v_add_f32_e32 v53, v76, v53
	v_add_f32_e32 v53, v75, v53
	v_lshlrev_b32_e32 v79, 16, v21
	v_lshlrev_b32_e32 v78, 16, v20
	v_and_b32_e32 v81, 0xffff0000, v21
	v_add_f32_e32 v53, v77, v53
	v_and_b32_e32 v80, 0xffff0000, v20
	v_mov_b32_e32 v82, v81
	v_mov_b32_e32 v83, v79
	v_fmac_f32_e32 v53, v78, v78
	v_pk_mul_f32 v[82:83], v[82:83], v[82:83]
	v_fmac_f32_e32 v53, v80, v80
	v_and_b32_e32 v44, 0xffff0000, v22
	v_lshlrev_b32_e32 v45, 16, v22
	v_add_f32_e32 v53, v83, v53
	v_pk_mul_f32 v[40:41], v[44:45], v[44:45]
	v_add_f32_e32 v53, v82, v53
	v_and_b32_e32 v46, 0xffff0000, v23
	v_lshlrev_b32_e32 v47, 16, v23
	v_add_f32_e32 v41, v41, v53
	v_pk_mul_f32 v[42:43], v[46:47], v[46:47]
	v_add_f32_e32 v40, v40, v41
	v_add_f32_e32 v40, v43, v40
	v_add_f32_e32 v40, v42, v40
	s_waitcnt lgkmcnt(0)
	s_nop 1
	v_add_f32_dpp v40, v40, v40 quad_perm:[1,0,3,2] row_mask:0xf bank_mask:0xf
	s_waitcnt lgkmcnt(0)
	s_nop 1
	v_add_f32_dpp v40, v40, v40 quad_perm:[2,3,0,1] row_mask:0xf bank_mask:0xf
	s_waitcnt lgkmcnt(0)
	s_nop 1
	v_add_f32_dpp v40, v40, v40 row_half_mirror row_mask:0xf bank_mask:0xf
	s_waitcnt lgkmcnt(0)
	s_nop 1
	v_add_f32_dpp v40, v40, v40 row_mirror row_mask:0xf bank_mask:0xf
	v_fmamk_f32 v40, v40, 0x3b800000, v165
	v_mul_f32_e32 v41, 0x4b800000, v40
	v_cmp_gt_f32_e64 s[40:41], s9, v40
	s_nop 1
	v_cndmask_b32_e64 v40, v40, v41, s[40:41]
	v_rsq_f32_e32 v42, v40
	v_lshlrev_b64 v[40:41], 11, v[56:57]
	v_lshl_add_u64 v[56:57], v[48:49], 0, v[40:41]
	v_mul_f32_e32 v40, 0x45800000, v42
	v_cndmask_b32_e64 v66, v42, v40, s[40:41]
	v_pk_mul_f32 v[42:43], v[66:67], v[64:65] op_sel_hi:[0,1]
	v_pk_mul_f32 v[64:65], v[66:67], v[72:73] op_sel_hi:[0,1]
	v_pk_mul_f32 v[40:41], v[66:67], v[58:59] op_sel_hi:[0,1]
	v_pk_mul_f32 v[42:43], v[50:51], v[42:43]
	v_pk_mul_f32 v[58:59], v[66:67], v[70:71] op_sel_hi:[0,1]
	v_pk_mul_f32 v[64:65], v[4:5], v[64:65]
	v_pk_mul_f32 v[40:41], v[2:3], v[40:41]
	v_pk_mul_f32 v[58:59], v[6:7], v[58:59]
	v_pk_mul_f32 v[68:69], v[66:67], v[78:79] op_sel_hi:[0,1]
	v_pk_mul_f32 v[70:71], v[66:67], v[80:81] op_sel_hi:[0,1]
	v_bfe_u32 v53, v65, 16, 1
	v_bfe_u32 v63, v64, 16, 1
	v_bfe_u32 v67, v43, 16, 1
	v_bfe_u32 v72, v42, 16, 1
	v_add3_u32 v72, v42, v72, s84
	v_add3_u32 v67, v43, v67, s84
	v_add3_u32 v42, v64, v63, s84
	v_add3_u32 v43, v65, v53, s84
	v_bfe_u32 v53, v40, 16, 1
	v_bfe_u32 v63, v41, 16, 1
	v_bfe_u32 v64, v58, 16, 1
	v_bfe_u32 v65, v59, 16, 1
	v_add3_u32 v59, v59, v65, s84
	v_add3_u32 v58, v58, v64, s84
	v_add3_u32 v41, v41, v63, s84
	v_add3_u32 v40, v40, v53, s84
	v_lshrrev_b32_e32 v40, 16, v40
	v_lshrrev_b32_e32 v41, 16, v41
	v_lshrrev_b32_e32 v53, 16, v58
	v_lshrrev_b32_e32 v58, 16, v59
	v_and_or_b32 v43, v43, s3, v58
	v_and_or_b32 v42, v42, s3, v53
	v_and_or_b32 v41, v67, s3, v41
	v_and_or_b32 v40, v72, s3, v40
	global_store_dwordx4 v[56:57], v[40:43], off
	v_pk_mul_f32 v[68:69], v[10:11], v[68:69]
	v_pk_mul_f32 v[70:71], v[8:9], v[70:71]
	v_mov_b32_e32 v40, v45
	v_mov_b32_e32 v45, v46
	v_mov_b32_e32 v41, v47
	v_pk_mul_f32 v[42:43], v[66:67], v[44:45] op_sel_hi:[0,1]
	v_pk_mul_f32 v[40:41], v[66:67], v[40:41] op_sel_hi:[0,1]
	v_pk_mul_f32 v[42:43], v[12:13], v[42:43]
	v_pk_mul_f32 v[40:41], v[14:15], v[40:41]
	v_bfe_u32 v44, v43, 16, 1
	v_bfe_u32 v45, v42, 16, 1
	v_add3_u32 v42, v42, v45, s84
	v_add3_u32 v43, v43, v44, s84
	v_bfe_u32 v44, v68, 16, 1
	v_bfe_u32 v45, v69, 16, 1
	v_bfe_u32 v53, v40, 16, 1
	v_bfe_u32 v58, v41, 16, 1
	v_bfe_u32 v46, v71, 16, 1
	v_bfe_u32 v47, v70, 16, 1
	v_add3_u32 v41, v41, v58, s84
	v_add3_u32 v40, v40, v53, s84
	v_add3_u32 v45, v69, v45, s84
	v_add3_u32 v44, v68, v44, s84
	v_add3_u32 v47, v70, v47, s84
	v_add3_u32 v46, v71, v46, s84
	v_lshrrev_b32_e32 v44, 16, v44
	v_lshrrev_b32_e32 v45, 16, v45
	v_lshrrev_b32_e32 v40, 16, v40
	v_lshrrev_b32_e32 v41, 16, v41
	v_and_or_b32 v43, v43, s3, v41
	v_and_or_b32 v42, v42, s3, v40
	v_and_or_b32 v41, v46, s3, v45
	v_and_or_b32 v40, v47, s3, v44
	global_store_dwordx4 v[56:57], v[40:43], off offset:16
	s_or_b64 exec, exec, s[36:37]
	s_and_saveexec_b64 s[36:37], vcc
	s_cbranch_execz .LBB0_169
; __device__ __forceinline__ u32x4 pack8(const float* f) { u32x4 o; o.x = pk2(f[0], f[1]); o.y = pk2(f[2], f[3]); o.z = pk2(f[4], f[5]); o.w = pk2(f[6], f[7]); return o; }
; __device__ __forceinline__ void phase_norm(bf16* Y, const float* g, int tid) {
;     ...
;         for (int u = 0; u < 4; ++u) { const int t = t0 + u * NGW; if (t < T) {
;             bf16* row = Y + (size_t)t * DM + lane * 16;
;             float y[16];
;             unpack8(ya[u][0], y); unpack8(ya[u][1], y + 8);
;             float ss = 0.f;
; #pragma unroll
;             for (int i = 0; i < 16; ++i) ss += y[i] * y[i];
;             ss += __shfl_xor(ss, 1); ss += __shfl_xor(ss, 2); ss += __shfl_xor(ss, 4); ss += __shfl_xor(ss, 8);
;             const float r = rsqrtf(ss * (1.f / 256.f) + 1e-6f);
; #pragma unroll
;             for (int i = 0; i < 16; ++i) y[i] = y[i] * r * gg[i];
;             *(u32x4*)row = pack8(y); *(u32x4*)(row + 8) = pack8(y + 8); } }
.LBB0_181:
	s_waitcnt vmcnt(6)
	v_lshlrev_b32_e32 v57, 16, v25
	v_lshlrev_b32_e32 v56, 16, v24
	v_and_b32_e32 v59, 0xffff0000, v25
	v_and_b32_e32 v58, 0xffff0000, v24
	v_pk_mul_f32 v[64:65], v[56:57], v[56:57]
	v_pk_mul_f32 v[66:67], v[58:59], v[58:59]
	v_lshlrev_b32_e32 v69, 16, v27
	v_add_f32_e32 v53, v64, v66
	v_lshlrev_b32_e32 v68, 16, v26
	v_add_f32_e32 v53, v65, v53
	v_and_b32_e32 v71, 0xffff0000, v27
	v_and_b32_e32 v70, 0xffff0000, v26
	v_pk_mul_f32 v[72:73], v[68:69], v[68:69]
	v_add_f32_e32 v53, v67, v53
	v_pk_mul_f32 v[74:75], v[70:71], v[70:71]
	v_add_f32_e32 v53, v72, v53
	v_add_f32_e32 v53, v74, v53
	v_add_f32_e32 v53, v73, v53
	v_lshlrev_b32_e32 v77, 16, v17
	v_lshlrev_b32_e32 v76, 16, v16
	v_and_b32_e32 v79, 0xffff0000, v17
	v_add_f32_e32 v53, v75, v53
	v_and_b32_e32 v78, 0xffff0000, v16
	v_mov_b32_e32 v80, v79
	v_mov_b32_e32 v81, v77
	v_fmac_f32_e32 v53, v76, v76
	v_pk_mul_f32 v[80:81], v[80:81], v[80:81]
	v_fmac_f32_e32 v53, v78, v78
	v_and_b32_e32 v44, 0xffff0000, v18
	v_lshlrev_b32_e32 v45, 16, v18
	v_add_f32_e32 v53, v81, v53
	v_pk_mul_f32 v[40:41], v[44:45], v[44:45]
	v_add_f32_e32 v53, v80, v53
	v_and_b32_e32 v46, 0xffff0000, v19
	v_lshlrev_b32_e32 v47, 16, v19
	v_add_f32_e32 v41, v41, v53
	v_pk_mul_f32 v[42:43], v[46:47], v[46:47]
	v_add_f32_e32 v40, v40, v41
	v_add_f32_e32 v40, v43, v40
	v_add_f32_e32 v40, v42, v40
	s_waitcnt lgkmcnt(0)
	s_nop 1
	v_add_f32_dpp v40, v40, v40 quad_perm:[1,0,3,2] row_mask:0xf bank_mask:0xf
	s_waitcnt lgkmcnt(0)
	s_nop 1
	v_add_f32_dpp v40, v40, v40 quad_perm:[2,3,0,1] row_mask:0xf bank_mask:0xf
	s_waitcnt lgkmcnt(0)
	s_nop 1
	v_add_f32_dpp v40, v40, v40 row_half_mirror row_mask:0xf bank_mask:0xf
	s_waitcnt lgkmcnt(0)
	s_nop 1
	v_add_f32_dpp v40, v40, v40 row_mirror row_mask:0xf bank_mask:0xf
	v_fmamk_f32 v40, v40, 0x3b800000, v165
	v_mul_f32_e32 v41, 0x4b800000, v40
	v_cmp_gt_f32_e32 vcc, s9, v40
	s_nop 1
	v_cndmask_b32_e32 v40, v40, v41, vcc
	v_rsq_f32_e32 v42, v40
	v_lshlrev_b64 v[40:41], 11, v[54:55]
	v_lshl_add_u64 v[54:55], v[48:49], 0, v[40:41]
	v_mul_f32_e32 v40, 0x45800000, v42
	v_cndmask_b32_e32 v64, v42, v40, vcc
	v_pk_mul_f32 v[42:43], v[64:65], v[58:59] op_sel_hi:[0,1]
	v_pk_mul_f32 v[58:59], v[64:65], v[70:71] op_sel_hi:[0,1]
	v_pk_mul_f32 v[40:41], v[64:65], v[56:57] op_sel_hi:[0,1]
	v_pk_mul_f32 v[42:43], v[50:51], v[42:43]
	v_pk_mul_f32 v[56:57], v[64:65], v[68:69] op_sel_hi:[0,1]
	v_pk_mul_f32 v[58:59], v[4:5], v[58:59]
	v_pk_mul_f32 v[40:41], v[2:3], v[40:41]
	v_pk_mul_f32 v[56:57], v[6:7], v[56:57]
	v_pk_mul_f32 v[66:67], v[64:65], v[76:77] op_sel_hi:[0,1]
	v_pk_mul_f32 v[68:69], v[64:65], v[78:79] op_sel_hi:[0,1]
	v_bfe_u32 v53, v59, 16, 1
	v_bfe_u32 v63, v58, 16, 1
	v_bfe_u32 v65, v43, 16, 1
	v_bfe_u32 v70, v42, 16, 1
	v_add3_u32 v70, v42, v70, s84
	v_add3_u32 v65, v43, v65, s84
	v_add3_u32 v42, v58, v63, s84
	v_add3_u32 v43, v59, v53, s84
	v_bfe_u32 v53, v40, 16, 1
	v_bfe_u32 v58, v41, 16, 1
	v_bfe_u32 v59, v56, 16, 1
	v_bfe_u32 v63, v57, 16, 1
	v_add3_u32 v57, v57, v63, s84
	v_add3_u32 v56, v56, v59, s84
	v_add3_u32 v41, v41, v58, s84
	v_add3_u32 v40, v40, v53, s84
	v_lshrrev_b32_e32 v40, 16, v40
	v_lshrrev_b32_e32 v41, 16, v41
	v_lshrrev_b32_e32 v53, 16, v56
	v_lshrrev_b32_e32 v56, 16, v57
	v_and_or_b32 v43, v43, s3, v56
	v_and_or_b32 v42, v42, s3, v53
	v_and_or_b32 v41, v65, s3, v41
	v_and_or_b32 v40, v70, s3, v40
	global_store_dwordx4 v[54:55], v[40:43], off
	v_pk_mul_f32 v[66:67], v[10:11], v[66:67]
	v_pk_mul_f32 v[68:69], v[8:9], v[68:69]
	v_mov_b32_e32 v40, v45
	v_mov_b32_e32 v45, v46
	v_mov_b32_e32 v41, v47
	v_pk_mul_f32 v[42:43], v[64:65], v[44:45] op_sel_hi:[0,1]
	v_pk_mul_f32 v[40:41], v[64:65], v[40:41] op_sel_hi:[0,1]
	v_pk_mul_f32 v[42:43], v[12:13], v[42:43]
	v_pk_mul_f32 v[40:41], v[14:15], v[40:41]
	v_bfe_u32 v44, v43, 16, 1
	v_bfe_u32 v45, v42, 16, 1
	v_add3_u32 v42, v42, v45, s84
	v_add3_u32 v43, v43, v44, s84
	v_bfe_u32 v44, v66, 16, 1
	v_bfe_u32 v45, v67, 16, 1
	v_bfe_u32 v53, v40, 16, 1
	v_bfe_u32 v56, v41, 16, 1
	v_bfe_u32 v46, v69, 16, 1
	v_bfe_u32 v47, v68, 16, 1
	v_add3_u32 v41, v41, v56, s84
	v_add3_u32 v40, v40, v53, s84
	v_add3_u32 v45, v67, v45, s84
	v_add3_u32 v44, v66, v44, s84
	v_add3_u32 v47, v68, v47, s84
	v_add3_u32 v46, v69, v46, s84
	v_lshrrev_b32_e32 v44, 16, v44
	v_lshrrev_b32_e32 v45, 16, v45
	v_lshrrev_b32_e32 v40, 16, v40
	v_lshrrev_b32_e32 v41, 16, v41
	v_and_or_b32 v43, v43, s3, v41
	v_and_or_b32 v42, v42, s3, v40
	v_and_or_b32 v41, v46, s3, v45
	v_and_or_b32 v40, v47, s3, v44
	global_store_dwordx4 v[54:55], v[40:43], off offset:16
	s_branch .LBB0_169

; __device__ __forceinline__ unsigned pk2(float lo, float hi) { return f2bf(lo) | (f2bf(hi) << 16); }
; __device__ __forceinline__ void phase_prologue(CArgs& A, unsigned char* lds, int tid) {
;     ...
;         for (int u = 0; u < 4; ++u) { const int r = it + u * NGW; if (r < R_ALL) {
;             bf16* dst = (r < R_X) ? ((bf16*)(ws + WS_X) + (size_t)r * DM) : ((bf16*)(ws + WS_Y) + (size_t)(r - R_X) * DM);
; #pragma unroll
;             for (int j = 0; j < 4; ++j) { u32x2 w; w.x = pk2(fv[u][j].x, fv[u][j].y); w.y = pk2(fv[u][j].z, fv[u][j].w); *(u32x2*)(dst + lane * 4 + 256 * j) = w; }
;             if (r < R_X) { float a0 = 0.f, a1 = 0.f, a2 = 0.f, a3 = 0.f;
; #pragma unroll
;                 for (int j = 0; j < 4; ++j)
; #pragma unroll
;                     for (int e = 0; e < 4; ++e) { const int d = lane * 4 + 256 * j + e; const f32x4 w = *(const f32x4*)(wf + 4 * d + 4 * (d >> 3)); const float xv = fv[u][j][e];
;                         a0 += xv * w.x; a1 += xv * w.y; a2 += xv * w.z; a3 += xv * w.w; }
;                 a0 = wave_sum(a0); a1 = wave_sum(a1); a2 = wave_sum(a2); a3 = wave_sum(a3);
;                 if (lane == 0) *(f32x4*)((float*)(ws + WS_FLOG) + (size_t)r * 4) = (f32x4){a0, a1, a2, a3}; } } }
.LBB0_503:
	s_or_b64 exec, exec, s[58:59]
	v_mov_b32_e32 v88, s7
	v_mov_b32_e32 v89, s17
	v_cndmask_b32_e64 v89, v88, v89, s[46:47]
	v_mov_b32_e32 v88, s6
	v_mov_b32_e32 v99, s16
	v_cndmask_b32_e64 v88, v88, v99, s[46:47]
	v_lshlrev_b64 v[84:85], 11, v[84:85]
	v_lshl_add_u64 v[88:89], v[88:89], 0, v[84:85]
	v_lshlrev_b32_e32 v84, 1, v72
	v_mov_b32_e32 v85, v0
	v_lshl_add_u64 v[88:89], v[88:89], 0, v[84:85]
	s_cmp_lg_u64 s[40:41], 0
	s_cbranch_scc1 .Lpx_rowfast
	s_waitcnt vmcnt(0)
.Lpx_rowfast:
	s_waitcnt vmcnt(15)
	v_bfe_u32 v85, v62, 16, 1
	v_add3_u32 v85, v62, v85, s84
	v_bfe_u32 v99, v63, 16, 1
	v_lshrrev_b32_e32 v85, 16, v85
	v_add3_u32 v99, v63, v99, s84
	v_and_or_b32 v100, v99, s3, v85
	v_bfe_u32 v85, v64, 16, 1
	v_add3_u32 v85, v64, v85, s84
	v_bfe_u32 v99, v65, 16, 1
	v_lshrrev_b32_e32 v85, 16, v85
	v_add3_u32 v99, v65, v99, s84
	v_and_or_b32 v101, v99, s3, v85
	s_waitcnt vmcnt(14)
	v_bfe_u32 v85, v58, 16, 1
	v_add3_u32 v85, v58, v85, s84
	v_bfe_u32 v99, v59, 16, 1
	v_lshrrev_b32_e32 v85, 16, v85
	v_add3_u32 v99, v59, v99, s84
	global_store_dwordx2 v[88:89], v[100:101], off
	v_and_or_b32 v100, v99, s3, v85
	v_bfe_u32 v85, v60, 16, 1
	v_add3_u32 v85, v60, v85, s84
	v_bfe_u32 v99, v61, 16, 1
	v_lshrrev_b32_e32 v85, 16, v85
	v_add3_u32 v99, v61, v99, s84
	v_and_or_b32 v101, v99, s3, v85
	s_waitcnt vmcnt(14)
	v_bfe_u32 v85, v54, 16, 1
	v_add3_u32 v85, v54, v85, s84
	v_bfe_u32 v99, v55, 16, 1
	v_lshrrev_b32_e32 v85, 16, v85
	v_add3_u32 v99, v55, v99, s84
	global_store_dwordx2 v[88:89], v[100:101], off offset:512
	v_and_or_b32 v100, v99, s3, v85
	v_bfe_u32 v85, v56, 16, 1
	v_add3_u32 v85, v56, v85, s84
	v_bfe_u32 v99, v57, 16, 1
	v_lshrrev_b32_e32 v85, 16, v85
	v_add3_u32 v99, v57, v99, s84
	v_and_or_b32 v101, v99, s3, v85
	s_waitcnt vmcnt(14)
	v_bfe_u32 v85, v50, 16, 1
	v_add3_u32 v85, v50, v85, s84
	v_bfe_u32 v99, v51, 16, 1
	v_lshrrev_b32_e32 v85, 16, v85
	v_add3_u32 v99, v51, v99, s84
	global_store_dwordx2 v[88:89], v[100:101], off offset:1024
	v_and_or_b32 v100, v99, s3, v85
	v_bfe_u32 v85, v52, 16, 1
	v_add3_u32 v85, v52, v85, s84
	v_bfe_u32 v99, v53, 16, 1
	v_lshrrev_b32_e32 v85, 16, v85
	v_add3_u32 v99, v53, v99, s84
	v_and_or_b32 v101, v99, s3, v85
	global_store_dwordx2 v[88:89], v[100:101], off offset:1536
	s_and_saveexec_b64 s[48:49], s[46:47]
	s_cbranch_execz .LBB0_506
	v_add_u32_e32 v85, v1, v67
	ds_read_b128 v[100:103], v85
	ds_read_b128 v[104:107], v85 offset:16
	ds_read_b128 v[108:111], v85 offset:32
	ds_read_b128 v[112:115], v85 offset:48
	v_add_u32_e32 v85, v69, v73
	v_add_u32_e32 v88, v69, v67
	ds_read_b128 v[116:119], v85
	ds_read_b128 v[120:123], v88 offset:4112
	ds_read_b128 v[124:127], v88 offset:4128
	ds_read_b128 v[128:131], v88 offset:4144
	v_add_u32_e32 v85, v90, v91
	v_add_u32_e32 v88, v90, v67
	ds_read_b128 v[132:135], v85
	ds_read_b128 v[136:139], v88 offset:8208
	ds_read_b128 v[140:143], v88 offset:8224
	ds_read_b128 v[144:147], v88 offset:8240
	s_waitcnt lgkmcnt(11)
	v_pk_fma_f32 v[88:89], v[62:63], v[100:101], 0 op_sel_hi:[0,1,0]
	v_pk_fma_f32 v[102:103], v[62:63], v[102:103], 0 op_sel_hi:[0,1,0]
	s_waitcnt lgkmcnt(10)
	v_pk_fma_f32 v[88:89], v[62:63], v[104:105], v[88:89] op_sel:[1,0,0]
	v_pk_fma_f32 v[62:63], v[62:63], v[106:107], v[102:103] op_sel:[1,0,0]
	s_waitcnt lgkmcnt(9)
	v_pk_fma_f32 v[88:89], v[64:65], v[108:109], v[88:89] op_sel_hi:[0,1,1]
	v_mov_b32_e32 v100, v65
	v_pk_fma_f32 v[62:63], v[64:65], v[110:111], v[62:63] op_sel_hi:[0,1,1]
	s_waitcnt lgkmcnt(8)
	v_pk_fma_f32 v[88:89], v[100:101], v[112:113], v[88:89] op_sel_hi:[0,1,1]
	v_pk_fma_f32 v[62:63], v[100:101], v[114:115], v[62:63] op_sel_hi:[0,1,1]
	s_waitcnt lgkmcnt(7)
	v_pk_fma_f32 v[88:89], v[58:59], v[116:117], v[88:89] op_sel_hi:[0,1,1]
	v_pk_fma_f32 v[62:63], v[58:59], v[118:119], v[62:63] op_sel_hi:[0,1,1]
	s_waitcnt lgkmcnt(6)
	v_pk_fma_f32 v[88:89], v[58:59], v[120:121], v[88:89] op_sel:[1,0,0]
	v_pk_fma_f32 v[58:59], v[58:59], v[122:123], v[62:63] op_sel:[1,0,0]
	s_waitcnt lgkmcnt(5)
	v_pk_fma_f32 v[88:89], v[60:61], v[124:125], v[88:89] op_sel_hi:[0,1,1]
	v_mov_b32_e32 v104, v61
	v_pk_fma_f32 v[58:59], v[60:61], v[126:127], v[58:59] op_sel_hi:[0,1,1]
	s_waitcnt lgkmcnt(4)
	v_pk_fma_f32 v[88:89], v[104:105], v[128:129], v[88:89] op_sel_hi:[0,1,1]
	v_pk_fma_f32 v[58:59], v[104:105], v[130:131], v[58:59] op_sel_hi:[0,1,1]
	s_waitcnt lgkmcnt(3)
	v_pk_fma_f32 v[88:89], v[54:55], v[132:133], v[88:89] op_sel_hi:[0,1,1]
	v_pk_fma_f32 v[58:59], v[54:55], v[134:135], v[58:59] op_sel_hi:[0,1,1]
	s_waitcnt lgkmcnt(2)
	v_pk_fma_f32 v[88:89], v[54:55], v[136:137], v[88:89] op_sel:[1,0,0]
	v_pk_fma_f32 v[54:55], v[54:55], v[138:139], v[58:59] op_sel:[1,0,0]
	v_add_u32_e32 v85, v92, v67
	s_waitcnt lgkmcnt(1)
	v_pk_fma_f32 v[104:105], v[56:57], v[142:143], v[54:55] op_sel_hi:[0,1,1]
	v_add_u32_e32 v54, v92, v93
	v_cmp_lt_i32_e64 s[46:47], v174, v173
	v_pk_fma_f32 v[88:89], v[56:57], v[140:141], v[88:89] op_sel_hi:[0,1,1]
	v_mov_b32_e32 v106, v57
	ds_read_b128 v[54:57], v54
	ds_read_b128 v[58:61], v85 offset:12304
	ds_read_b128 v[62:65], v85 offset:12320
	ds_read_b128 v[100:103], v85 offset:12336
	v_cndmask_b32_e64 v85, v167, v174, s[46:47]
	v_cmp_lt_i32_e64 s[46:47], v175, v173
	v_lshlrev_b32_e32 v85, 2, v85
	s_nop 0
	v_cndmask_b32_e64 v99, v167, v175, s[46:47]
	v_cmp_lt_i32_e64 s[46:47], v176, v173
	v_lshlrev_b32_e32 v99, 2, v99
	s_nop 0
	v_cndmask_b32_e64 v107, v167, v176, s[46:47]
	v_lshlrev_b32_e32 v107, 2, v107
	s_waitcnt lgkmcnt(4)
	v_pk_fma_f32 v[88:89], v[106:107], v[144:145], v[88:89] op_sel_hi:[0,1,1]
	s_waitcnt lgkmcnt(3)
; __device__ __forceinline__ unsigned pk2(float lo, float hi) { return f2bf(lo) | (f2bf(hi) << 16); }
; __device__ __forceinline__ void phase_prologue(CArgs& A, unsigned char* lds, int tid) {
;     ...
;         for (int u = 0; u < 4; ++u) { const int r = it + u * NGW; if (r < R_ALL) {
;             bf16* dst = (r < R_X) ? ((bf16*)(ws + WS_X) + (size_t)r * DM) : ((bf16*)(ws + WS_Y) + (size_t)(r - R_X) * DM);
; #pragma unroll
;             for (int j = 0; j < 4; ++j) { u32x2 w; w.x = pk2(fv[u][j].x, fv[u][j].y); w.y = pk2(fv[u][j].z, fv[u][j].w); *(u32x2*)(dst + lane * 4 + 256 * j) = w; }
;             if (r < R_X) { float a0 = 0.f, a1 = 0.f, a2 = 0.f, a3 = 0.f;
; #pragma unroll
;                 for (int j = 0; j < 4; ++j)
; #pragma unroll
;                     for (int e = 0; e < 4; ++e) { const int d = lane * 4 + 256 * j + e; const f32x4 w = *(const f32x4*)(wf + 4 * d + 4 * (d >> 3)); const float xv = fv[u][j][e];
;                         a0 += xv * w.x; a1 += xv * w.y; a2 += xv * w.z; a3 += xv * w.w; }
;                 a0 = wave_sum(a0); a1 = wave_sum(a1); a2 = wave_sum(a2); a3 = wave_sum(a3);
;                 if (lane == 0) *(f32x4*)((float*)(ws + WS_FLOG) + (size_t)r * 4) = (f32x4){a0, a1, a2, a3}; } } }
	v_pk_fma_f32 v[54:55], v[50:51], v[54:55], v[88:89] op_sel_hi:[0,1,1]
	v_pk_fma_f32 v[88:89], v[106:107], v[146:147], v[104:105] op_sel_hi:[0,1,1]
	v_pk_fma_f32 v[56:57], v[50:51], v[56:57], v[88:89] op_sel_hi:[0,1,1]
	s_waitcnt lgkmcnt(2)
	v_pk_fma_f32 v[54:55], v[50:51], v[58:59], v[54:55] op_sel:[1,0,0]
	v_pk_fma_f32 v[50:51], v[50:51], v[60:61], v[56:57] op_sel:[1,0,0]
	s_waitcnt lgkmcnt(1)
	v_pk_fma_f32 v[54:55], v[52:53], v[62:63], v[54:55] op_sel_hi:[0,1,1]
	v_mov_b32_e32 v58, v53
	v_pk_fma_f32 v[50:51], v[52:53], v[64:65], v[50:51] op_sel_hi:[0,1,1]
	s_waitcnt lgkmcnt(0)
	v_pk_fma_f32 v[54:55], v[58:59], v[100:101], v[54:55] op_sel_hi:[0,1,1]
	v_pk_fma_f32 v[50:51], v[58:59], v[102:103], v[50:51] op_sel_hi:[0,1,1]
	ds_bpermute_b32 v62, v85, v54
	ds_bpermute_b32 v63, v85, v55
	ds_bpermute_b32 v52, v85, v50
	ds_bpermute_b32 v53, v85, v51
	v_cmp_lt_i32_e64 s[46:47], v177, v173
	s_waitcnt lgkmcnt(2)
	v_pk_add_f32 v[54:55], v[54:55], v[62:63]
	ds_bpermute_b32 v56, v99, v54
	s_waitcnt lgkmcnt(1)
	v_pk_add_f32 v[50:51], v[50:51], v[52:53]
	ds_bpermute_b32 v57, v99, v55
	ds_bpermute_b32 v52, v99, v50
	ds_bpermute_b32 v53, v99, v51
	v_cndmask_b32_e64 v108, v167, v177, s[46:47]
	v_lshlrev_b32_e32 v58, 2, v108
	s_waitcnt lgkmcnt(2)
	v_pk_add_f32 v[54:55], v[54:55], v[56:57]
	ds_bpermute_b32 v56, v107, v54
	s_waitcnt lgkmcnt(1)
	v_pk_add_f32 v[50:51], v[50:51], v[52:53]
	ds_bpermute_b32 v57, v107, v55
	ds_bpermute_b32 v52, v107, v50
	ds_bpermute_b32 v53, v107, v51
	v_cmp_lt_i32_e64 s[46:47], v178, v173
	s_waitcnt lgkmcnt(2)
	v_pk_add_f32 v[54:55], v[54:55], v[56:57]
	ds_bpermute_b32 v56, v58, v54
	s_waitcnt lgkmcnt(1)
	v_pk_add_f32 v[50:51], v[50:51], v[52:53]
	ds_bpermute_b32 v57, v58, v55
	ds_bpermute_b32 v52, v58, v50
	ds_bpermute_b32 v53, v58, v51
	v_cndmask_b32_e64 v59, v167, v178, s[46:47]
	v_lshlrev_b32_e32 v61, 2, v59
	s_waitcnt lgkmcnt(2)
	v_pk_add_f32 v[54:55], v[54:55], v[56:57]
	ds_bpermute_b32 v56, v61, v54
	s_waitcnt lgkmcnt(1)
	v_pk_add_f32 v[58:59], v[50:51], v[52:53]
	ds_bpermute_b32 v57, v61, v55
	ds_bpermute_b32 v60, v61, v58
	ds_bpermute_b32 v61, v61, v59
	v_cmp_lt_i32_e64 s[46:47], v179, v173
	s_waitcnt lgkmcnt(2)
	v_pk_add_f32 v[50:51], v[54:55], v[56:57]
	v_cndmask_b32_e64 v62, v167, v179, s[46:47]
	v_lshlrev_b32_e32 v62, 2, v62
	s_waitcnt lgkmcnt(0)
	v_pk_add_f32 v[54:55], v[58:59], v[60:61]
	ds_bpermute_b32 v52, v62, v50
	ds_bpermute_b32 v53, v62, v51
	ds_bpermute_b32 v56, v62, v54
	ds_bpermute_b32 v57, v62, v55
	s_and_b64 exec, exec, vcc
	s_cbranch_execz .LBB0_506
	v_lshl_add_u64 v[58:59], s[56:57], 0, v[78:79]
	s_waitcnt lgkmcnt(0)
	v_pk_add_f32 v[54:55], v[54:55], v[56:57]
	v_pk_add_f32 v[52:53], v[50:51], v[52:53]
	global_store_dwordx4 v[58:59], v[52:55], off
.LBB0_506:
	s_or_b64 exec, exec, s[48:49]
	s_and_saveexec_b64 s[46:47], s[44:45]
	s_cbranch_execz .LBB0_510
	s_waitcnt vmcnt(12)
	v_cmp_gt_i32_e64 s[44:45], s19, v97
	s_waitcnt lgkmcnt(3)
	v_mov_b32_e32 v52, s7
	s_waitcnt lgkmcnt(2)
	v_mov_b32_e32 v53, s17
	v_cndmask_b32_e64 v51, 0, v87, s[44:45]
	v_cndmask_b32_e64 v50, v98, v86, s[44:45]
	v_cndmask_b32_e64 v53, v52, v53, s[44:45]
	v_mov_b32_e32 v52, s6
	v_mov_b32_e32 v54, s16
	v_cndmask_b32_e64 v52, v52, v54, s[44:45]
	v_lshlrev_b64 v[50:51], 11, v[50:51]
	v_lshl_add_u64 v[50:51], v[52:53], 0, v[50:51]
	v_bfe_u32 v52, v46, 16, 1
	v_add3_u32 v52, v46, v52, s84
	v_bfe_u32 v53, v47, 16, 1
	v_lshrrev_b32_e32 v52, 16, v52
	v_add3_u32 v53, v47, v53, s84
	v_and_or_b32 v52, v53, s3, v52
	v_bfe_u32 v53, v48, 16, 1
	v_add3_u32 v53, v48, v53, s84
	v_bfe_u32 v54, v49, 16, 1
	v_mov_b32_e32 v85, v0
	v_lshrrev_b32_e32 v53, 16, v53
	v_add3_u32 v54, v49, v54, s84
	v_lshl_add_u64 v[50:51], v[50:51], 0, v[84:85]
	v_and_or_b32 v53, v54, s3, v53
	global_store_dwordx2 v[50:51], v[52:53], off
	v_bfe_u32 v52, v42, 16, 1
	v_add3_u32 v52, v42, v52, s84
	v_bfe_u32 v53, v43, 16, 1
	v_lshrrev_b32_e32 v52, 16, v52
	v_add3_u32 v53, v43, v53, s84
	v_and_or_b32 v52, v53, s3, v52
	v_bfe_u32 v53, v44, 16, 1
	v_add3_u32 v53, v44, v53, s84
	v_bfe_u32 v54, v45, 16, 1
	v_lshrrev_b32_e32 v53, 16, v53
	v_add3_u32 v54, v45, v54, s84
	v_and_or_b32 v53, v54, s3, v53
	global_store_dwordx2 v[50:51], v[52:53], off offset:512
	v_bfe_u32 v52, v38, 16, 1
	v_add3_u32 v52, v38, v52, s84
	v_bfe_u32 v53, v39, 16, 1
	v_lshrrev_b32_e32 v52, 16, v52
	v_add3_u32 v53, v39, v53, s84
	v_and_or_b32 v52, v53, s3, v52
	v_bfe_u32 v53, v40, 16, 1
	v_add3_u32 v53, v40, v53, s84
	v_bfe_u32 v54, v41, 16, 1
	v_lshrrev_b32_e32 v53, 16, v53
	v_add3_u32 v54, v41, v54, s84
	v_and_or_b32 v53, v54, s3, v53
	global_store_dwordx2 v[50:51], v[52:53], off offset:1024
	v_bfe_u32 v52, v34, 16, 1
	v_add3_u32 v52, v34, v52, s84
	v_bfe_u32 v53, v35, 16, 1
	v_lshrrev_b32_e32 v52, 16, v52
	v_add3_u32 v53, v35, v53, s84
	v_and_or_b32 v52, v53, s3, v52
	v_bfe_u32 v53, v36, 16, 1
	v_add3_u32 v53, v36, v53, s84
	v_bfe_u32 v54, v37, 16, 1
	v_lshrrev_b32_e32 v53, 16, v53
	v_add3_u32 v54, v37, v54, s84
	v_and_or_b32 v53, v54, s3, v53
	global_store_dwordx2 v[50:51], v[52:53], off offset:1536
	s_and_b64 exec, exec, s[44:45]
	s_cbranch_execz .LBB0_510
; __device__ __forceinline__ void phase_prologue(CArgs& A, unsigned char* lds, int tid) {
;     ...
;             if (r < R_X) { float a0 = 0.f, a1 = 0.f, a2 = 0.f, a3 = 0.f;
; #pragma unroll
;                 for (int j = 0; j < 4; ++j)
; #pragma unroll
;                     for (int e = 0; e < 4; ++e) { const int d = lane * 4 + 256 * j + e; const f32x4 w = *(const f32x4*)(wf + 4 * d + 4 * (d >> 3)); const float xv = fv[u][j][e];
;                         a0 += xv * w.x; a1 += xv * w.y; a2 += xv * w.z; a3 += xv * w.w; }
;                 a0 = wave_sum(a0); a1 = wave_sum(a1); a2 = wave_sum(a2); a3 = wave_sum(a3);
;                 if (lane == 0) *(f32x4*)((float*)(ws + WS_FLOG) + (size_t)r * 4) = (f32x4){a0, a1, a2, a3}; } } }
	v_add_u32_e32 v62, v1, v67
	ds_read_b128 v[50:53], v62
	s_waitcnt lgkmcnt(1)
	ds_read_b128 v[54:57], v62 offset:16
	ds_read_b128 v[58:61], v62 offset:32
	ds_read_b128 v[62:65], v62 offset:48
	v_add_u32_e32 v85, v69, v73
	s_waitcnt lgkmcnt(3)
	v_pk_fma_f32 v[50:51], v[46:47], v[50:51], 0 op_sel_hi:[0,1,0]
	s_waitcnt lgkmcnt(2)
	v_pk_fma_f32 v[50:51], v[46:47], v[54:55], v[50:51] op_sel:[1,0,0]
	v_add_u32_e32 v97, v69, v67
	ds_read_b128 v[86:89], v85
	ds_read_b128 v[98:101], v97 offset:4112
	ds_read_b128 v[102:105], v97 offset:4128
	ds_read_b128 v[106:109], v97 offset:4144
	s_waitcnt lgkmcnt(5)
	v_pk_fma_f32 v[50:51], v[48:49], v[58:59], v[50:51] op_sel_hi:[0,1,1]
	v_mov_b32_e32 v54, v49
	s_waitcnt lgkmcnt(4)
	v_pk_fma_f32 v[50:51], v[54:55], v[62:63], v[50:51] op_sel_hi:[0,1,1]
	s_waitcnt lgkmcnt(3)
	v_pk_fma_f32 v[50:51], v[42:43], v[86:87], v[50:51] op_sel_hi:[0,1,1]
	v_add_u32_e32 v85, v90, v91
	s_waitcnt lgkmcnt(2)
	v_pk_fma_f32 v[50:51], v[42:43], v[98:99], v[50:51] op_sel:[1,0,0]
	v_add_u32_e32 v97, v90, v67
	ds_read_b128 v[110:113], v85
	ds_read_b128 v[114:117], v97 offset:8208
	ds_read_b128 v[118:121], v97 offset:8224
	ds_read_b128 v[122:125], v97 offset:8240
	s_waitcnt lgkmcnt(5)
	v_pk_fma_f32 v[50:51], v[44:45], v[102:103], v[50:51] op_sel_hi:[0,1,1]
	v_mov_b32_e32 v58, v45
	s_waitcnt lgkmcnt(4)
	v_pk_fma_f32 v[50:51], v[58:59], v[106:107], v[50:51] op_sel_hi:[0,1,1]
	s_waitcnt lgkmcnt(3)
	v_pk_fma_f32 v[50:51], v[38:39], v[110:111], v[50:51] op_sel_hi:[0,1,1]
	s_waitcnt lgkmcnt(2)
	v_pk_fma_f32 v[50:51], v[38:39], v[114:115], v[50:51] op_sel:[1,0,0]
	v_cmp_lt_i32_e64 s[44:45], v174, v173
	s_waitcnt lgkmcnt(1)
	v_pk_fma_f32 v[86:87], v[40:41], v[118:119], v[50:51] op_sel_hi:[0,1,1]
	v_pk_fma_f32 v[50:51], v[46:47], v[52:53], 0 op_sel_hi:[0,1,0]
	v_pk_fma_f32 v[50:51], v[46:47], v[56:57], v[50:51] op_sel:[1,0,0]
	v_cndmask_b32_e64 v85, v167, v174, s[44:45]
	v_pk_fma_f32 v[50:51], v[48:49], v[60:61], v[50:51] op_sel_hi:[0,1,1]
	v_pk_fma_f32 v[50:51], v[54:55], v[64:65], v[50:51] op_sel_hi:[0,1,1]
	v_pk_fma_f32 v[50:51], v[42:43], v[88:89], v[50:51] op_sel_hi:[0,1,1]
	v_pk_fma_f32 v[50:51], v[42:43], v[100:101], v[50:51] op_sel:[1,0,0]
	v_cmp_lt_i32_e64 s[44:45], v175, v173
	v_pk_fma_f32 v[50:51], v[44:45], v[104:105], v[50:51] op_sel_hi:[0,1,1]
	v_pk_fma_f32 v[50:51], v[58:59], v[108:109], v[50:51] op_sel_hi:[0,1,1]
	v_pk_fma_f32 v[50:51], v[38:39], v[112:113], v[50:51] op_sel_hi:[0,1,1]
	v_pk_fma_f32 v[50:51], v[38:39], v[116:117], v[50:51] op_sel:[1,0,0]
	v_cndmask_b32_e64 v97, v167, v175, s[44:45]
	v_cmp_lt_i32_e64 s[44:45], v176, v173
	v_pk_fma_f32 v[88:89], v[40:41], v[120:121], v[50:51] op_sel_hi:[0,1,1]
	v_add_u32_e32 v50, v92, v93
	v_add_u32_e32 v62, v92, v67
	v_cndmask_b32_e64 v99, v167, v176, s[44:45]
	v_mov_b32_e32 v98, v41
	ds_read_b128 v[50:53], v50
	ds_read_b128 v[54:57], v62 offset:12304
	ds_read_b128 v[58:61], v62 offset:12320
	ds_read_b128 v[62:65], v62 offset:12336
	v_lshlrev_b32_e32 v99, 2, v99
	s_waitcnt lgkmcnt(4)
	v_pk_fma_f32 v[86:87], v[98:99], v[122:123], v[86:87] op_sel_hi:[0,1,1]
	s_waitcnt lgkmcnt(3)
	v_pk_fma_f32 v[50:51], v[34:35], v[50:51], v[86:87] op_sel_hi:[0,1,1]
	s_waitcnt lgkmcnt(2)
	v_pk_fma_f32 v[50:51], v[34:35], v[54:55], v[50:51] op_sel:[1,0,0]
	v_mov_b32_e32 v54, v37
	s_waitcnt lgkmcnt(1)
	v_pk_fma_f32 v[50:51], v[36:37], v[58:59], v[50:51] op_sel_hi:[0,1,1]
	s_waitcnt lgkmcnt(0)
	v_pk_fma_f32 v[50:51], v[54:55], v[62:63], v[50:51] op_sel_hi:[0,1,1]
	v_pk_fma_f32 v[62:63], v[98:99], v[124:125], v[88:89] op_sel_hi:[0,1,1]
	v_pk_fma_f32 v[52:53], v[34:35], v[52:53], v[62:63] op_sel_hi:[0,1,1]
	v_pk_fma_f32 v[52:53], v[34:35], v[56:57], v[52:53] op_sel:[1,0,0]
	v_lshlrev_b32_e32 v85, 2, v85
	v_pk_fma_f32 v[52:53], v[36:37], v[60:61], v[52:53] op_sel_hi:[0,1,1]
	v_pk_fma_f32 v[52:53], v[54:55], v[64:65], v[52:53] op_sel_hi:[0,1,1]
	ds_bpermute_b32 v58, v85, v50
	ds_bpermute_b32 v59, v85, v51
	ds_bpermute_b32 v54, v85, v52
	ds_bpermute_b32 v55, v85, v53
	v_lshlrev_b32_e32 v97, 2, v97
	v_cmp_lt_i32_e64 s[44:45], v177, v173
	s_waitcnt lgkmcnt(2)
	v_pk_add_f32 v[50:51], v[50:51], v[58:59]
	ds_bpermute_b32 v56, v97, v50
	s_waitcnt lgkmcnt(1)
	v_pk_add_f32 v[52:53], v[52:53], v[54:55]
	ds_bpermute_b32 v57, v97, v51
	ds_bpermute_b32 v54, v97, v52
	ds_bpermute_b32 v55, v97, v53
	v_cndmask_b32_e64 v100, v167, v177, s[44:45]
	v_lshlrev_b32_e32 v60, 2, v100
	s_waitcnt lgkmcnt(2)
	v_pk_add_f32 v[50:51], v[50:51], v[56:57]
	ds_bpermute_b32 v56, v99, v50
	s_waitcnt lgkmcnt(1)
	v_pk_add_f32 v[52:53], v[52:53], v[54:55]
	ds_bpermute_b32 v57, v99, v51
	ds_bpermute_b32 v54, v99, v52
	ds_bpermute_b32 v55, v99, v53
	v_cmp_lt_i32_e64 s[44:45], v178, v173
	s_waitcnt lgkmcnt(2)
	v_pk_add_f32 v[50:51], v[50:51], v[56:57]
	ds_bpermute_b32 v56, v60, v50
	s_waitcnt lgkmcnt(1)
	v_pk_add_f32 v[52:53], v[52:53], v[54:55]
	ds_bpermute_b32 v57, v60, v51
	ds_bpermute_b32 v54, v60, v52
	ds_bpermute_b32 v55, v60, v53
	v_cndmask_b32_e64 v58, v167, v178, s[44:45]
	v_lshlrev_b32_e32 v59, 2, v58
	s_waitcnt lgkmcnt(2)
	v_pk_add_f32 v[50:51], v[50:51], v[56:57]
	ds_bpermute_b32 v56, v59, v50
	s_waitcnt lgkmcnt(1)
	v_pk_add_f32 v[54:55], v[52:53], v[54:55]
	ds_bpermute_b32 v57, v59, v51
	ds_bpermute_b32 v58, v59, v54
	ds_bpermute_b32 v59, v59, v55
	v_cmp_lt_i32_e64 s[44:45], v179, v173
	s_waitcnt lgkmcnt(2)
	v_pk_add_f32 v[50:51], v[50:51], v[56:57]
	v_cndmask_b32_e64 v60, v167, v179, s[44:45]
	v_lshlrev_b32_e32 v60, 2, v60
	s_waitcnt lgkmcnt(0)
	v_pk_add_f32 v[54:55], v[54:55], v[58:59]
	ds_bpermute_b32 v52, v60, v50
	ds_bpermute_b32 v53, v60, v51
	ds_bpermute_b32 v56, v60, v54
	ds_bpermute_b32 v57, v60, v55
	s_and_b64 exec, exec, vcc
	s_cbranch_execz .LBB0_510
	v_lshl_add_u64 v[58:59], s[56:57], 0, v[76:77]
	s_waitcnt lgkmcnt(0)
	v_pk_add_f32 v[54:55], v[54:55], v[56:57]
	v_pk_add_f32 v[52:53], v[50:51], v[52:53]
	global_store_dwordx4 v[58:59], v[52:55], off
; __device__ __forceinline__ unsigned pk2(float lo, float hi) { return f2bf(lo) | (f2bf(hi) << 16); }
; __device__ __forceinline__ void phase_prologue(CArgs& A, unsigned char* lds, int tid) {
;     ...
;         for (int u = 0; u < 4; ++u) { const int r = it + u * NGW; if (r < R_ALL) {
;             bf16* dst = (r < R_X) ? ((bf16*)(ws + WS_X) + (size_t)r * DM) : ((bf16*)(ws + WS_Y) + (size_t)(r - R_X) * DM);
; #pragma unroll
;             for (int j = 0; j < 4; ++j) { u32x2 w; w.x = pk2(fv[u][j].x, fv[u][j].y); w.y = pk2(fv[u][j].z, fv[u][j].w); *(u32x2*)(dst + lane * 4 + 256 * j) = w; }
;             if (r < R_X) { float a0 = 0.f, a1 = 0.f, a2 = 0.f, a3 = 0.f;
; #pragma unroll
;                 for (int j = 0; j < 4; ++j)
; #pragma unroll
;                     for (int e = 0; e < 4; ++e) { const int d = lane * 4 + 256 * j + e; const f32x4 w = *(const f32x4*)(wf + 4 * d + 4 * (d >> 3)); const float xv = fv[u][j][e];
;                         a0 += xv * w.x; a1 += xv * w.y; a2 += xv * w.z; a3 += xv * w.w; }
;                 a0 = wave_sum(a0); a1 = wave_sum(a1); a2 = wave_sum(a2); a3 = wave_sum(a3);
;                 if (lane == 0) *(f32x4*)((float*)(ws + WS_FLOG) + (size_t)r * 4) = (f32x4){a0, a1, a2, a3}; } } }
.LBB0_510:
	s_or_b64 exec, exec, s[46:47]
	s_and_saveexec_b64 s[44:45], s[42:43]
	s_cbranch_execz .LBB0_514
	s_waitcnt vmcnt(12)
	v_cmp_gt_i32_e64 s[42:43], s19, v82
	s_waitcnt lgkmcnt(3)
	v_mov_b32_e32 v52, s7
	s_waitcnt lgkmcnt(2)
	v_mov_b32_e32 v53, s17
	v_cndmask_b32_e64 v51, 0, v83, s[42:43]
	v_cndmask_b32_e64 v50, v96, v82, s[42:43]
	v_cndmask_b32_e64 v53, v52, v53, s[42:43]
	v_mov_b32_e32 v52, s6
	v_mov_b32_e32 v54, s16
	v_cndmask_b32_e64 v52, v52, v54, s[42:43]
	v_lshlrev_b64 v[50:51], 11, v[50:51]
	v_lshl_add_u64 v[50:51], v[52:53], 0, v[50:51]
	v_bfe_u32 v52, v30, 16, 1
	v_add3_u32 v52, v30, v52, s84
	v_bfe_u32 v53, v31, 16, 1
	v_lshrrev_b32_e32 v52, 16, v52
	v_add3_u32 v53, v31, v53, s84
	v_and_or_b32 v52, v53, s3, v52
	v_bfe_u32 v53, v32, 16, 1
	v_add3_u32 v53, v32, v53, s84
	v_bfe_u32 v54, v33, 16, 1
	v_mov_b32_e32 v85, v0
	v_lshrrev_b32_e32 v53, 16, v53
	v_add3_u32 v54, v33, v54, s84
	v_lshl_add_u64 v[50:51], v[50:51], 0, v[84:85]
	v_and_or_b32 v53, v54, s3, v53
	global_store_dwordx2 v[50:51], v[52:53], off
	v_bfe_u32 v52, v26, 16, 1
	v_add3_u32 v52, v26, v52, s84
	v_bfe_u32 v53, v27, 16, 1
	v_lshrrev_b32_e32 v52, 16, v52
	v_add3_u32 v53, v27, v53, s84
	v_and_or_b32 v52, v53, s3, v52
	v_bfe_u32 v53, v28, 16, 1
	v_add3_u32 v53, v28, v53, s84
	v_bfe_u32 v54, v29, 16, 1
	v_lshrrev_b32_e32 v53, 16, v53
	v_add3_u32 v54, v29, v54, s84
	v_and_or_b32 v53, v54, s3, v53
	global_store_dwordx2 v[50:51], v[52:53], off offset:512
	v_bfe_u32 v52, v22, 16, 1
	v_add3_u32 v52, v22, v52, s84
	v_bfe_u32 v53, v23, 16, 1
	v_lshrrev_b32_e32 v52, 16, v52
	v_add3_u32 v53, v23, v53, s84
	v_and_or_b32 v52, v53, s3, v52
	v_bfe_u32 v53, v24, 16, 1
	v_add3_u32 v53, v24, v53, s84
	v_bfe_u32 v54, v25, 16, 1
	v_lshrrev_b32_e32 v53, 16, v53
	v_add3_u32 v54, v25, v54, s84
	v_and_or_b32 v53, v54, s3, v53
	global_store_dwordx2 v[50:51], v[52:53], off offset:1024
	v_bfe_u32 v52, v18, 16, 1
	v_add3_u32 v52, v18, v52, s84
	v_bfe_u32 v53, v19, 16, 1
	v_lshrrev_b32_e32 v52, 16, v52
	v_add3_u32 v53, v19, v53, s84
	v_and_or_b32 v52, v53, s3, v52
	v_bfe_u32 v53, v20, 16, 1
	v_add3_u32 v53, v20, v53, s84
	v_bfe_u32 v54, v21, 16, 1
	v_lshrrev_b32_e32 v53, 16, v53
	v_add3_u32 v54, v21, v54, s84
	v_and_or_b32 v53, v54, s3, v53
	global_store_dwordx2 v[50:51], v[52:53], off offset:1536
	s_and_b64 exec, exec, s[42:43]
	s_cbranch_execz .LBB0_514
	v_add_u32_e32 v62, v1, v67
	ds_read_b128 v[50:53], v62
	s_waitcnt lgkmcnt(1)
	ds_read_b128 v[54:57], v62 offset:16
	ds_read_b128 v[58:61], v62 offset:32
	ds_read_b128 v[62:65], v62 offset:48
	v_add_u32_e32 v85, v69, v73
	s_waitcnt lgkmcnt(3)
	v_pk_fma_f32 v[50:51], v[30:31], v[50:51], 0 op_sel_hi:[0,1,0]
	v_add_u32_e32 v104, v69, v67
	s_waitcnt lgkmcnt(2)
	v_pk_fma_f32 v[50:51], v[30:31], v[54:55], v[50:51] op_sel:[1,0,0]
	ds_read_b128 v[86:89], v85
	ds_read_b128 v[96:99], v104 offset:4112
	ds_read_b128 v[100:103], v104 offset:4128
	ds_read_b128 v[104:107], v104 offset:4144
	s_waitcnt lgkmcnt(5)
	v_pk_fma_f32 v[50:51], v[32:33], v[58:59], v[50:51] op_sel_hi:[0,1,1]
	v_mov_b32_e32 v54, v33
	s_waitcnt lgkmcnt(4)
	v_pk_fma_f32 v[50:51], v[54:55], v[62:63], v[50:51] op_sel_hi:[0,1,1]
	s_waitcnt lgkmcnt(3)
	v_pk_fma_f32 v[50:51], v[26:27], v[86:87], v[50:51] op_sel_hi:[0,1,1]
	v_add_u32_e32 v85, v90, v91
	v_add_u32_e32 v120, v90, v67
	s_waitcnt lgkmcnt(2)
	v_pk_fma_f32 v[50:51], v[26:27], v[96:97], v[50:51] op_sel:[1,0,0]
	ds_read_b128 v[108:111], v85
	ds_read_b128 v[112:115], v120 offset:8208
	ds_read_b128 v[116:119], v120 offset:8224
	ds_read_b128 v[120:123], v120 offset:8240
	s_waitcnt lgkmcnt(5)
	v_pk_fma_f32 v[50:51], v[28:29], v[100:101], v[50:51] op_sel_hi:[0,1,1]
	v_mov_b32_e32 v58, v29
	s_waitcnt lgkmcnt(4)
	v_pk_fma_f32 v[50:51], v[58:59], v[104:105], v[50:51] op_sel_hi:[0,1,1]
	s_waitcnt lgkmcnt(3)
	v_pk_fma_f32 v[50:51], v[22:23], v[108:109], v[50:51] op_sel_hi:[0,1,1]
	s_waitcnt lgkmcnt(2)
	v_pk_fma_f32 v[50:51], v[22:23], v[112:113], v[50:51] op_sel:[1,0,0]
	v_cmp_lt_i32_e64 s[42:43], v174, v173
	s_waitcnt lgkmcnt(1)
	v_pk_fma_f32 v[86:87], v[24:25], v[116:117], v[50:51] op_sel_hi:[0,1,1]
	v_pk_fma_f32 v[50:51], v[30:31], v[52:53], 0 op_sel_hi:[0,1,0]
	v_pk_fma_f32 v[50:51], v[30:31], v[56:57], v[50:51] op_sel:[1,0,0]
	v_cndmask_b32_e64 v85, v167, v174, s[42:43]
	v_pk_fma_f32 v[50:51], v[32:33], v[60:61], v[50:51] op_sel_hi:[0,1,1]
	v_pk_fma_f32 v[50:51], v[54:55], v[64:65], v[50:51] op_sel_hi:[0,1,1]
	v_pk_fma_f32 v[50:51], v[26:27], v[88:89], v[50:51] op_sel_hi:[0,1,1]
	v_pk_fma_f32 v[50:51], v[26:27], v[98:99], v[50:51] op_sel:[1,0,0]
	v_cmp_lt_i32_e64 s[42:43], v175, v173
	v_pk_fma_f32 v[50:51], v[28:29], v[102:103], v[50:51] op_sel_hi:[0,1,1]
	v_pk_fma_f32 v[50:51], v[58:59], v[106:107], v[50:51] op_sel_hi:[0,1,1]
	v_pk_fma_f32 v[50:51], v[22:23], v[110:111], v[50:51] op_sel_hi:[0,1,1]
	v_pk_fma_f32 v[50:51], v[22:23], v[114:115], v[50:51] op_sel:[1,0,0]
	v_add_u32_e32 v62, v92, v67
	v_pk_fma_f32 v[88:89], v[24:25], v[118:119], v[50:51] op_sel_hi:[0,1,1]
	v_add_u32_e32 v50, v92, v93
	v_cndmask_b32_e64 v97, v167, v175, s[42:43]
	v_mov_b32_e32 v96, v25
	ds_read_b128 v[50:53], v50
	ds_read_b128 v[54:57], v62 offset:12304
	ds_read_b128 v[58:61], v62 offset:12320
	ds_read_b128 v[62:65], v62 offset:12336
	v_lshlrev_b32_e32 v97, 2, v97
	s_waitcnt lgkmcnt(4)
	v_pk_fma_f32 v[86:87], v[96:97], v[120:121], v[86:87] op_sel_hi:[0,1,1]
	s_waitcnt lgkmcnt(3)
	v_pk_fma_f32 v[50:51], v[18:19], v[50:51], v[86:87] op_sel_hi:[0,1,1]
	s_waitcnt lgkmcnt(2)
	v_pk_fma_f32 v[50:51], v[18:19], v[54:55], v[50:51] op_sel:[1,0,0]
	v_mov_b32_e32 v54, v21
	s_waitcnt lgkmcnt(1)
	v_pk_fma_f32 v[50:51], v[20:21], v[58:59], v[50:51] op_sel_hi:[0,1,1]
	s_waitcnt lgkmcnt(0)
; __device__ __forceinline__ unsigned pk2(float lo, float hi) { return f2bf(lo) | (f2bf(hi) << 16); }
; __device__ __forceinline__ void phase_prologue(CArgs& A, unsigned char* lds, int tid) {
;     ...
;         for (int u = 0; u < 4; ++u) { const int r = it + u * NGW; if (r < R_ALL) {
;             bf16* dst = (r < R_X) ? ((bf16*)(ws + WS_X) + (size_t)r * DM) : ((bf16*)(ws + WS_Y) + (size_t)(r - R_X) * DM);
; #pragma unroll
;             for (int j = 0; j < 4; ++j) { u32x2 w; w.x = pk2(fv[u][j].x, fv[u][j].y); w.y = pk2(fv[u][j].z, fv[u][j].w); *(u32x2*)(dst + lane * 4 + 256 * j) = w; }
;             if (r < R_X) { float a0 = 0.f, a1 = 0.f, a2 = 0.f, a3 = 0.f;
; #pragma unroll
;                 for (int j = 0; j < 4; ++j)
; #pragma unroll
;                     for (int e = 0; e < 4; ++e) { const int d = lane * 4 + 256 * j + e; const f32x4 w = *(const f32x4*)(wf + 4 * d + 4 * (d >> 3)); const float xv = fv[u][j][e];
;                         a0 += xv * w.x; a1 += xv * w.y; a2 += xv * w.z; a3 += xv * w.w; }
;                 a0 = wave_sum(a0); a1 = wave_sum(a1); a2 = wave_sum(a2); a3 = wave_sum(a3);
;                 if (lane == 0) *(f32x4*)((float*)(ws + WS_FLOG) + (size_t)r * 4) = (f32x4){a0, a1, a2, a3}; } } }
	v_pk_fma_f32 v[50:51], v[54:55], v[62:63], v[50:51] op_sel_hi:[0,1,1]
	v_pk_fma_f32 v[62:63], v[96:97], v[122:123], v[88:89] op_sel_hi:[0,1,1]
	v_pk_fma_f32 v[52:53], v[18:19], v[52:53], v[62:63] op_sel_hi:[0,1,1]
	v_pk_fma_f32 v[52:53], v[18:19], v[56:57], v[52:53] op_sel:[1,0,0]
	v_lshlrev_b32_e32 v85, 2, v85
	v_pk_fma_f32 v[52:53], v[20:21], v[60:61], v[52:53] op_sel_hi:[0,1,1]
	v_pk_fma_f32 v[52:53], v[54:55], v[64:65], v[52:53] op_sel_hi:[0,1,1]
	ds_bpermute_b32 v58, v85, v50
	ds_bpermute_b32 v59, v85, v51
	ds_bpermute_b32 v54, v85, v52
	ds_bpermute_b32 v55, v85, v53
	v_cmp_lt_i32_e64 s[42:43], v176, v173
	s_waitcnt lgkmcnt(2)
	v_pk_add_f32 v[50:51], v[50:51], v[58:59]
	ds_bpermute_b32 v56, v97, v50
	s_waitcnt lgkmcnt(1)
	v_pk_add_f32 v[52:53], v[52:53], v[54:55]
	ds_bpermute_b32 v57, v97, v51
	ds_bpermute_b32 v54, v97, v52
	ds_bpermute_b32 v55, v97, v53
	v_cndmask_b32_e64 v98, v167, v176, s[42:43]
	v_lshlrev_b32_e32 v98, 2, v98
	s_waitcnt lgkmcnt(2)
	v_pk_add_f32 v[50:51], v[50:51], v[56:57]
	ds_bpermute_b32 v56, v98, v50
	s_waitcnt lgkmcnt(1)
	v_pk_add_f32 v[52:53], v[52:53], v[54:55]
	ds_bpermute_b32 v57, v98, v51
	ds_bpermute_b32 v54, v98, v52
	ds_bpermute_b32 v55, v98, v53
	v_cmp_lt_i32_e64 s[42:43], v177, v173
	s_waitcnt lgkmcnt(2)
	v_pk_add_f32 v[50:51], v[50:51], v[56:57]
	v_cndmask_b32_e64 v99, v167, v177, s[42:43]
	v_lshlrev_b32_e32 v60, 2, v99
	s_waitcnt lgkmcnt(0)
	v_pk_add_f32 v[52:53], v[52:53], v[54:55]
	ds_bpermute_b32 v56, v60, v50
	ds_bpermute_b32 v57, v60, v51
	ds_bpermute_b32 v54, v60, v52
	ds_bpermute_b32 v55, v60, v53
	v_cmp_lt_i32_e64 s[42:43], v178, v173
	s_waitcnt lgkmcnt(2)
	v_pk_add_f32 v[50:51], v[50:51], v[56:57]
	v_cndmask_b32_e64 v58, v167, v178, s[42:43]
	v_lshlrev_b32_e32 v59, 2, v58
	s_waitcnt lgkmcnt(0)
	v_pk_add_f32 v[54:55], v[52:53], v[54:55]
	ds_bpermute_b32 v56, v59, v50
	ds_bpermute_b32 v57, v59, v51
	ds_bpermute_b32 v58, v59, v54
	ds_bpermute_b32 v59, v59, v55
	v_cmp_lt_i32_e64 s[42:43], v179, v173
	s_waitcnt lgkmcnt(2)
	v_pk_add_f32 v[50:51], v[50:51], v[56:57]
	v_cndmask_b32_e64 v60, v167, v179, s[42:43]
	v_lshlrev_b32_e32 v60, 2, v60
	s_waitcnt lgkmcnt(0)
	v_pk_add_f32 v[54:55], v[54:55], v[58:59]
	ds_bpermute_b32 v52, v60, v50
	ds_bpermute_b32 v53, v60, v51
	ds_bpermute_b32 v56, v60, v54
	ds_bpermute_b32 v57, v60, v55
	s_and_b64 exec, exec, vcc
	s_cbranch_execz .LBB0_514
	v_lshl_add_u64 v[58:59], v[82:83], 4, s[8:9]
	s_waitcnt lgkmcnt(0)
	v_pk_add_f32 v[54:55], v[54:55], v[56:57]
	v_pk_add_f32 v[52:53], v[50:51], v[52:53]
	global_store_dwordx4 v[58:59], v[52:55], off
.LBB0_514:
	s_or_b64 exec, exec, s[44:45]
	s_and_saveexec_b64 s[42:43], s[40:41]
	s_cbranch_execz .LBB0_496
	s_waitcnt vmcnt(12)
	v_cmp_gt_i32_e64 s[40:41], s19, v80
	s_waitcnt lgkmcnt(3)
	v_mov_b32_e32 v52, s7
	s_waitcnt lgkmcnt(2)
	v_mov_b32_e32 v53, s17
	v_cndmask_b32_e64 v51, 0, v81, s[40:41]
	v_cndmask_b32_e64 v50, v95, v80, s[40:41]
	v_cndmask_b32_e64 v53, v52, v53, s[40:41]
	v_mov_b32_e32 v52, s6
	v_mov_b32_e32 v54, s16
	v_cndmask_b32_e64 v52, v52, v54, s[40:41]
	v_lshlrev_b64 v[50:51], 11, v[50:51]
	v_lshl_add_u64 v[50:51], v[52:53], 0, v[50:51]
	v_bfe_u32 v52, v14, 16, 1
	v_add3_u32 v52, v14, v52, s84
	v_bfe_u32 v53, v15, 16, 1
	v_lshrrev_b32_e32 v52, 16, v52
	v_add3_u32 v53, v15, v53, s84
	v_and_or_b32 v52, v53, s3, v52
	v_bfe_u32 v53, v16, 16, 1
	v_add3_u32 v53, v16, v53, s84
	v_bfe_u32 v54, v17, 16, 1
	v_mov_b32_e32 v85, v0
	v_lshrrev_b32_e32 v53, 16, v53
	v_add3_u32 v54, v17, v54, s84
	v_lshl_add_u64 v[50:51], v[50:51], 0, v[84:85]
	v_and_or_b32 v53, v54, s3, v53
	global_store_dwordx2 v[50:51], v[52:53], off
	v_bfe_u32 v52, v10, 16, 1
	v_add3_u32 v52, v10, v52, s84
	v_bfe_u32 v53, v11, 16, 1
	v_lshrrev_b32_e32 v52, 16, v52
	v_add3_u32 v53, v11, v53, s84
	v_and_or_b32 v52, v53, s3, v52
	v_bfe_u32 v53, v12, 16, 1
	v_add3_u32 v53, v12, v53, s84
	v_bfe_u32 v54, v13, 16, 1
	v_lshrrev_b32_e32 v53, 16, v53
	v_add3_u32 v54, v13, v54, s84
	v_and_or_b32 v53, v54, s3, v53
	global_store_dwordx2 v[50:51], v[52:53], off offset:512
	v_bfe_u32 v52, v6, 16, 1
	v_add3_u32 v52, v6, v52, s84
	v_bfe_u32 v53, v7, 16, 1
	v_lshrrev_b32_e32 v52, 16, v52
	v_add3_u32 v53, v7, v53, s84
	v_and_or_b32 v52, v53, s3, v52
	v_bfe_u32 v53, v8, 16, 1
	v_add3_u32 v53, v8, v53, s84
	v_bfe_u32 v54, v9, 16, 1
	v_lshrrev_b32_e32 v53, 16, v53
	v_add3_u32 v54, v9, v54, s84
	v_and_or_b32 v53, v54, s3, v53
	global_store_dwordx2 v[50:51], v[52:53], off offset:1024
	v_bfe_u32 v52, v2, 16, 1
	v_add3_u32 v52, v2, v52, s84
	v_bfe_u32 v53, v3, 16, 1
	v_lshrrev_b32_e32 v52, 16, v52
	v_add3_u32 v53, v3, v53, s84
	v_and_or_b32 v52, v53, s3, v52
	v_bfe_u32 v53, v4, 16, 1
	v_add3_u32 v53, v4, v53, s84
	v_bfe_u32 v54, v5, 16, 1
	v_lshrrev_b32_e32 v53, 16, v53
	v_add3_u32 v54, v5, v54, s84
	v_and_or_b32 v53, v54, s3, v53
	global_store_dwordx2 v[50:51], v[52:53], off offset:1536
	s_and_b64 exec, exec, s[40:41]
	s_cbranch_execz .LBB0_496
; __device__ __forceinline__ void phase_prologue(CArgs& A, unsigned char* lds, int tid) {
;     ...
;             if (r < R_X) { float a0 = 0.f, a1 = 0.f, a2 = 0.f, a3 = 0.f;
; #pragma unroll
;                 for (int j = 0; j < 4; ++j)
; #pragma unroll
;                     for (int e = 0; e < 4; ++e) { const int d = lane * 4 + 256 * j + e; const f32x4 w = *(const f32x4*)(wf + 4 * d + 4 * (d >> 3)); const float xv = fv[u][j][e];
;                         a0 += xv * w.x; a1 += xv * w.y; a2 += xv * w.z; a3 += xv * w.w; }
;                 a0 = wave_sum(a0); a1 = wave_sum(a1); a2 = wave_sum(a2); a3 = wave_sum(a3);
;                 if (lane == 0) *(f32x4*)((float*)(ws + WS_FLOG) + (size_t)r * 4) = (f32x4){a0, a1, a2, a3}; } } }
	v_add_u32_e32 v62, v1, v67
	ds_read_b128 v[50:53], v62
	s_waitcnt lgkmcnt(1)
	ds_read_b128 v[54:57], v62 offset:16
	ds_read_b128 v[58:61], v62 offset:32
	ds_read_b128 v[62:65], v62 offset:48
	v_add_u32_e32 v82, v69, v73
	s_waitcnt lgkmcnt(3)
	v_pk_fma_f32 v[50:51], v[14:15], v[50:51], 0 op_sel_hi:[0,1,0]
	s_waitcnt lgkmcnt(2)
	v_pk_fma_f32 v[50:51], v[14:15], v[54:55], v[50:51] op_sel:[1,0,0]
	v_add_u32_e32 v95, v69, v67
	ds_read_b128 v[82:85], v82
	ds_read_b128 v[86:89], v95 offset:4112
	ds_read_b128 v[96:99], v95 offset:4128
	ds_read_b128 v[100:103], v95 offset:4144
	s_waitcnt lgkmcnt(5)
	v_pk_fma_f32 v[50:51], v[16:17], v[58:59], v[50:51] op_sel_hi:[0,1,1]
	v_mov_b32_e32 v54, v17
	s_waitcnt lgkmcnt(4)
	v_pk_fma_f32 v[50:51], v[54:55], v[62:63], v[50:51] op_sel_hi:[0,1,1]
	s_waitcnt lgkmcnt(3)
	v_pk_fma_f32 v[50:51], v[10:11], v[82:83], v[50:51] op_sel_hi:[0,1,1]
	v_add_u32_e32 v95, v90, v91
	v_add_u32_e32 v116, v90, v67
	s_waitcnt lgkmcnt(2)
	v_pk_fma_f32 v[50:51], v[10:11], v[86:87], v[50:51] op_sel:[1,0,0]
	ds_read_b128 v[104:107], v95
	ds_read_b128 v[108:111], v116 offset:8208
	ds_read_b128 v[112:115], v116 offset:8224
	ds_read_b128 v[116:119], v116 offset:8240
	s_waitcnt lgkmcnt(5)
	v_pk_fma_f32 v[50:51], v[12:13], v[96:97], v[50:51] op_sel_hi:[0,1,1]
	v_mov_b32_e32 v58, v13
	s_waitcnt lgkmcnt(4)
	v_pk_fma_f32 v[50:51], v[58:59], v[100:101], v[50:51] op_sel_hi:[0,1,1]
	s_waitcnt lgkmcnt(3)
	v_pk_fma_f32 v[50:51], v[6:7], v[104:105], v[50:51] op_sel_hi:[0,1,1]
	s_waitcnt lgkmcnt(2)
	v_pk_fma_f32 v[50:51], v[6:7], v[108:109], v[50:51] op_sel:[1,0,0]
	v_cmp_lt_i32_e64 s[40:41], v174, v173
	s_waitcnt lgkmcnt(1)
	v_pk_fma_f32 v[82:83], v[8:9], v[112:113], v[50:51] op_sel_hi:[0,1,1]
	v_pk_fma_f32 v[50:51], v[14:15], v[52:53], 0 op_sel_hi:[0,1,0]
	v_pk_fma_f32 v[50:51], v[14:15], v[56:57], v[50:51] op_sel:[1,0,0]
	v_add_u32_e32 v62, v92, v67
	v_pk_fma_f32 v[50:51], v[16:17], v[60:61], v[50:51] op_sel_hi:[0,1,1]
	v_pk_fma_f32 v[50:51], v[54:55], v[64:65], v[50:51] op_sel_hi:[0,1,1]
	v_pk_fma_f32 v[50:51], v[10:11], v[84:85], v[50:51] op_sel_hi:[0,1,1]
	v_pk_fma_f32 v[50:51], v[10:11], v[88:89], v[50:51] op_sel:[1,0,0]
	v_cndmask_b32_e64 v87, v167, v174, s[40:41]
	v_pk_fma_f32 v[50:51], v[12:13], v[98:99], v[50:51] op_sel_hi:[0,1,1]
	v_pk_fma_f32 v[50:51], v[58:59], v[102:103], v[50:51] op_sel_hi:[0,1,1]
	v_pk_fma_f32 v[50:51], v[6:7], v[106:107], v[50:51] op_sel_hi:[0,1,1]
	v_pk_fma_f32 v[50:51], v[6:7], v[110:111], v[50:51] op_sel:[1,0,0]
	v_mov_b32_e32 v86, v9
	v_pk_fma_f32 v[84:85], v[8:9], v[114:115], v[50:51] op_sel_hi:[0,1,1]
	v_add_u32_e32 v50, v92, v93
	ds_read_b128 v[50:53], v50
	ds_read_b128 v[54:57], v62 offset:12304
	ds_read_b128 v[58:61], v62 offset:12320
	ds_read_b128 v[62:65], v62 offset:12336
	v_lshlrev_b32_e32 v87, 2, v87
	s_waitcnt lgkmcnt(4)
	v_pk_fma_f32 v[82:83], v[86:87], v[116:117], v[82:83] op_sel_hi:[0,1,1]
	s_waitcnt lgkmcnt(3)
	v_pk_fma_f32 v[50:51], v[2:3], v[50:51], v[82:83] op_sel_hi:[0,1,1]
	s_waitcnt lgkmcnt(2)
	v_pk_fma_f32 v[50:51], v[2:3], v[54:55], v[50:51] op_sel:[1,0,0]
	v_mov_b32_e32 v54, v5
	s_waitcnt lgkmcnt(1)
	v_pk_fma_f32 v[50:51], v[4:5], v[58:59], v[50:51] op_sel_hi:[0,1,1]
	s_waitcnt lgkmcnt(0)
	v_pk_fma_f32 v[50:51], v[54:55], v[62:63], v[50:51] op_sel_hi:[0,1,1]
	v_pk_fma_f32 v[62:63], v[86:87], v[118:119], v[84:85] op_sel_hi:[0,1,1]
	v_pk_fma_f32 v[52:53], v[2:3], v[52:53], v[62:63] op_sel_hi:[0,1,1]
	v_pk_fma_f32 v[52:53], v[2:3], v[56:57], v[52:53] op_sel:[1,0,0]
	ds_bpermute_b32 v58, v87, v50
	v_pk_fma_f32 v[52:53], v[4:5], v[60:61], v[52:53] op_sel_hi:[0,1,1]
	v_pk_fma_f32 v[52:53], v[54:55], v[64:65], v[52:53] op_sel_hi:[0,1,1]
	ds_bpermute_b32 v59, v87, v51
	ds_bpermute_b32 v54, v87, v52
	ds_bpermute_b32 v55, v87, v53
	v_cmp_lt_i32_e64 s[40:41], v175, v173
	s_waitcnt lgkmcnt(2)
	v_pk_add_f32 v[50:51], v[50:51], v[58:59]
	v_cndmask_b32_e64 v88, v167, v175, s[40:41]
	v_lshlrev_b32_e32 v88, 2, v88
	s_waitcnt lgkmcnt(0)
	v_pk_add_f32 v[52:53], v[52:53], v[54:55]
	ds_bpermute_b32 v56, v88, v50
	ds_bpermute_b32 v57, v88, v51
	ds_bpermute_b32 v54, v88, v52
	ds_bpermute_b32 v55, v88, v53
	v_cmp_lt_i32_e64 s[40:41], v176, v173
	s_waitcnt lgkmcnt(2)
	v_pk_add_f32 v[50:51], v[50:51], v[56:57]
	v_cndmask_b32_e64 v89, v167, v176, s[40:41]
	v_lshlrev_b32_e32 v89, 2, v89
	s_waitcnt lgkmcnt(0)
	v_pk_add_f32 v[52:53], v[52:53], v[54:55]
	ds_bpermute_b32 v56, v89, v50
	ds_bpermute_b32 v57, v89, v51
	ds_bpermute_b32 v54, v89, v52
	ds_bpermute_b32 v55, v89, v53
	v_cmp_lt_i32_e64 s[40:41], v177, v173
	s_waitcnt lgkmcnt(2)
	v_pk_add_f32 v[50:51], v[50:51], v[56:57]
	v_cndmask_b32_e64 v95, v167, v177, s[40:41]
	v_lshlrev_b32_e32 v60, 2, v95
	s_waitcnt lgkmcnt(0)
	v_pk_add_f32 v[52:53], v[52:53], v[54:55]
	ds_bpermute_b32 v56, v60, v50
	ds_bpermute_b32 v57, v60, v51
	ds_bpermute_b32 v54, v60, v52
	ds_bpermute_b32 v55, v60, v53
	v_cmp_lt_i32_e64 s[40:41], v178, v173
	s_waitcnt lgkmcnt(2)
	v_pk_add_f32 v[50:51], v[50:51], v[56:57]
	v_cndmask_b32_e64 v58, v167, v178, s[40:41]
	v_lshlrev_b32_e32 v59, 2, v58
	s_waitcnt lgkmcnt(0)
	v_pk_add_f32 v[54:55], v[52:53], v[54:55]
	ds_bpermute_b32 v56, v59, v50
	ds_bpermute_b32 v57, v59, v51
	ds_bpermute_b32 v58, v59, v54
	ds_bpermute_b32 v59, v59, v55
	v_cmp_lt_i32_e64 s[40:41], v179, v173
	s_waitcnt lgkmcnt(2)
	v_pk_add_f32 v[50:51], v[50:51], v[56:57]
	v_cndmask_b32_e64 v60, v167, v179, s[40:41]
	v_lshlrev_b32_e32 v60, 2, v60
	s_waitcnt lgkmcnt(0)
	v_pk_add_f32 v[54:55], v[54:55], v[58:59]
	ds_bpermute_b32 v52, v60, v50
	ds_bpermute_b32 v53, v60, v51
	ds_bpermute_b32 v56, v60, v54
	ds_bpermute_b32 v57, v60, v55
	s_and_b64 exec, exec, vcc
	s_cbranch_execz .LBB0_496
	v_lshl_add_u64 v[58:59], v[80:81], 4, s[8:9]
	s_waitcnt lgkmcnt(0)
	v_pk_add_f32 v[54:55], v[54:55], v[56:57]
	v_pk_add_f32 v[52:53], v[50:51], v[52:53]
	global_store_dwordx4 v[58:59], v[52:55], off
	s_branch .LBB0_496

; __device__ __forceinline__ void phase_prologue(CArgs& A, unsigned char* lds, int tid) {
;     ...
;         for (int u = 0; u < 4; ++u) { const int r = it + u * NGW; if (r < 2 * R_U) {
;             {
;                 const float V_SC = (r < R_U) ? U_SCALE : V_SCALE;
;                 unsigned char* dst = (r < R_U) ? (ws + WS_U + (size_t)r * DM - lane * 8 + lane * 16) : (ws + WS_U + (size_t)(r - R_U) * DM - lane * 8 + lane * 16 + 8);
;                 const f32x4 a0 = rv[u][0] * V_SC, a1 = rv[u][1] * V_SC, a2 = rv[u][2] * V_SC, a3 = rv[u][3] * V_SC;
;                 unsigned w0 = 0u, w1 = 0u;
;                 if (r < R_U) {
;                     const float av[16] = {a0.x, a0.y, a0.z, a0.w, a1.x, a1.y, a1.z, a1.w, a2.x, a2.y, a2.z, a2.w, a3.x, a3.y, a3.z, a3.w};
; #pragma unroll
;                     for (int i = 0; i < 8; ++i) { const int q0 = (int)fminf(fmaxf(rintf(av[i]), -7.f), 7.f), q1 = (int)fminf(fmaxf(rintf(av[8 + i]), -7.f), 7.f);
;                         w0 |= ((unsigned)q0 & 0xFu) << (4 * i); w1 |= ((unsigned)q1 & 0xFu) << (4 * i); }
;                 } else {
;                 w0 = __builtin_amdgcn_cvt_scalef32_pk_fp4_f32(w0, a0.x, a0.y, 1.0f, 0); w0 = __builtin_amdgcn_cvt_scalef32_pk_fp4_f32(w0, a0.z, a0.w, 1.0f, 1);
;                 w0 = __builtin_amdgcn_cvt_scalef32_pk_fp4_f32(w0, a1.x, a1.y, 1.0f, 2); w0 = __builtin_amdgcn_cvt_scalef32_pk_fp4_f32(w0, a1.z, a1.w, 1.0f, 3);
;                 w1 = __builtin_amdgcn_cvt_scalef32_pk_fp4_f32(w1, a2.x, a2.y, 1.0f, 0); w1 = __builtin_amdgcn_cvt_scalef32_pk_fp4_f32(w1, a2.z, a2.w, 1.0f, 1);
;                 w1 = __builtin_amdgcn_cvt_scalef32_pk_fp4_f32(w1, a3.x, a3.y, 1.0f, 2); w1 = __builtin_amdgcn_cvt_scalef32_pk_fp4_f32(w1, a3.z, a3.w, 1.0f, 3);
;                 }
.LBB0_532:
	s_or_b64 exec, exec, s[6:7]
	v_cndmask_b32_e64 v84, v189, v190, s[46:47]
	s_cbranch_vccnz .Lpx_uvfast
	s_waitcnt vmcnt(0)
.Lpx_uvfast:
	s_waitcnt vmcnt(15)
	v_pk_mul_f32 v[64:65], v[64:65], v[84:85] op_sel_hi:[1,0]
	v_pk_mul_f32 v[70:71], v[62:63], v[84:85] op_sel_hi:[1,0]
	s_waitcnt vmcnt(14)
	v_pk_mul_f32 v[60:61], v[60:61], v[84:85] op_sel_hi:[1,0]
	v_pk_mul_f32 v[58:59], v[58:59], v[84:85] op_sel_hi:[1,0]
	s_waitcnt vmcnt(13)
	v_pk_mul_f32 v[56:57], v[56:57], v[84:85] op_sel_hi:[1,0]
	v_pk_mul_f32 v[62:63], v[54:55], v[84:85] op_sel_hi:[1,0]
	s_waitcnt vmcnt(12)
	v_pk_mul_f32 v[52:53], v[84:85], v[52:53] op_sel_hi:[0,1]
	v_pk_mul_f32 v[50:51], v[84:85], v[50:51] op_sel_hi:[0,1]
	s_and_saveexec_b64 s[6:7], s[44:45]
	s_xor_b64 s[6:7], exec, s[6:7]
	s_cbranch_execz .LBB0_534
	v_mov_b32_e32 v54, v0
	v_mov_b32_e32 v55, v0
	v_cvt_scalef32_pk_fp4_f32 v54, v70, v71, 1.0
	v_cvt_scalef32_pk_fp4_f32 v55, v62, v63, 1.0
	v_cvt_scalef32_pk_fp4_f32 v54, v64, v65, 1.0 op_sel:[0,0,1,0]
	v_cvt_scalef32_pk_fp4_f32 v55, v56, v57, 1.0 op_sel:[0,0,1,0]
	v_cvt_scalef32_pk_fp4_f32 v54, v58, v59, 1.0 op_sel:[0,0,0,1]
	v_cvt_scalef32_pk_fp4_f32 v55, v50, v51, 1.0 op_sel:[0,0,0,1]
	v_cvt_scalef32_pk_fp4_f32 v54, v60, v61, 1.0 op_sel:[0,0,1,1]
	v_cvt_scalef32_pk_fp4_f32 v55, v52, v53, 1.0 op_sel:[0,0,1,1]

; __device__ __forceinline__ void phase_prologue(CArgs& A, unsigned char* lds, int tid) {
;     ...
;         for (int u = 0; u < 4; ++u) { const int r = it + u * NGW; if (r < 2 * R_U) {
;             {
;                 const float V_SC = (r < R_U) ? U_SCALE : V_SCALE;
;                 unsigned char* dst = (r < R_U) ? (ws + WS_U + (size_t)r * DM - lane * 8 + lane * 16) : (ws + WS_U + (size_t)(r - R_U) * DM - lane * 8 + lane * 16 + 8);
;                 const f32x4 a0 = rv[u][0] * V_SC, a1 = rv[u][1] * V_SC, a2 = rv[u][2] * V_SC, a3 = rv[u][3] * V_SC;
;                 unsigned w0 = 0u, w1 = 0u;
;                 if (r < R_U) {
;                     const float av[16] = {a0.x, a0.y, a0.z, a0.w, a1.x, a1.y, a1.z, a1.w, a2.x, a2.y, a2.z, a2.w, a3.x, a3.y, a3.z, a3.w};
; #pragma unroll
;                     for (int i = 0; i < 8; ++i) { const int q0 = (int)fminf(fmaxf(rintf(av[i]), -7.f), 7.f), q1 = (int)fminf(fmaxf(rintf(av[8 + i]), -7.f), 7.f);
;                         w0 |= ((unsigned)q0 & 0xFu) << (4 * i); w1 |= ((unsigned)q1 & 0xFu) << (4 * i); }
;                 } else {
;                 w0 = __builtin_amdgcn_cvt_scalef32_pk_fp4_f32(w0, a0.x, a0.y, 1.0f, 0); w0 = __builtin_amdgcn_cvt_scalef32_pk_fp4_f32(w0, a0.z, a0.w, 1.0f, 1);
;                 w0 = __builtin_amdgcn_cvt_scalef32_pk_fp4_f32(w0, a1.x, a1.y, 1.0f, 2); w0 = __builtin_amdgcn_cvt_scalef32_pk_fp4_f32(w0, a1.z, a1.w, 1.0f, 3);
;                 w1 = __builtin_amdgcn_cvt_scalef32_pk_fp4_f32(w1, a2.x, a2.y, 1.0f, 0); w1 = __builtin_amdgcn_cvt_scalef32_pk_fp4_f32(w1, a2.z, a2.w, 1.0f, 1);
;                 w1 = __builtin_amdgcn_cvt_scalef32_pk_fp4_f32(w1, a3.x, a3.y, 1.0f, 2); w1 = __builtin_amdgcn_cvt_scalef32_pk_fp4_f32(w1, a3.z, a3.w, 1.0f, 3);
;                 }
;                 u32x2 o; o.x = w0; o.y = w1;
;                 *(u32x2*)(dst + lane * 8) = o;
.LBB0_536:
	s_or_b64 exec, exec, s[6:7]
	v_lshl_add_u64 v[50:51], v[82:83], 0, v[68:69]
	global_store_dwordx2 v[50:51], v[54:55], off
	s_and_saveexec_b64 s[6:7], s[42:43]
	s_cbranch_execz .LBB0_547
	s_waitcnt vmcnt(9)
	v_cmp_gt_i32_e64 s[44:45], s19, v76
	v_cmp_lt_i32_e64 s[42:43], s84, v76
	s_and_saveexec_b64 s[8:9], s[42:43]
	s_xor_b64 s[8:9], exec, s[8:9]
	v_add_u32_e32 v50, 0xffff8000, v76
	v_mov_b32_e32 v51, v0
	v_lshlrev_b64 v[50:51], 10, v[50:51]
	v_lshl_add_u64 v[50:51], v[72:73], 0, v[50:51]
	v_lshl_add_u64 v[50:51], v[50:51], 0, s[86:87]
	s_andn2_saveexec_b64 s[8:9], s[8:9]
	v_ashrrev_i32_e32 v77, 31, v76
	v_lshlrev_b64 v[50:51], 10, v[76:77]
	v_lshl_add_u64 v[50:51], v[74:75], 0, v[50:51]
	s_or_b64 exec, exec, s[8:9]
	v_cndmask_b32_e64 v56, v189, v190, s[44:45]
	v_pk_mul_f32 v[62:63], v[56:57], v[48:49] op_sel_hi:[0,1]
	v_pk_mul_f32 v[82:83], v[56:57], v[46:47] op_sel_hi:[0,1]
	v_pk_mul_f32 v[54:55], v[56:57], v[44:45] op_sel_hi:[0,1]
	v_pk_mul_f32 v[58:59], v[56:57], v[42:43] op_sel_hi:[0,1]
	v_pk_mul_f32 v[60:61], v[56:57], v[40:41] op_sel_hi:[0,1]
	v_pk_mul_f32 v[70:71], v[56:57], v[38:39] op_sel_hi:[0,1]
	v_pk_mul_f32 v[52:53], v[56:57], v[36:37] op_sel_hi:[0,1]
	v_pk_mul_f32 v[56:57], v[56:57], v[34:35] op_sel_hi:[0,1]
	s_and_saveexec_b64 s[8:9], s[42:43]
	s_xor_b64 s[8:9], exec, s[8:9]
	s_cbranch_execz .LBB0_543
	v_mov_b32_e32 v64, v0
	v_mov_b32_e32 v65, v0
	v_cvt_scalef32_pk_fp4_f32 v64, v82, v83, 1.0
	v_cvt_scalef32_pk_fp4_f32 v65, v70, v71, 1.0
	v_cvt_scalef32_pk_fp4_f32 v64, v62, v63, 1.0 op_sel:[0,0,1,0]
	v_cvt_scalef32_pk_fp4_f32 v65, v60, v61, 1.0 op_sel:[0,0,1,0]
	v_cvt_scalef32_pk_fp4_f32 v64, v58, v59, 1.0 op_sel:[0,0,0,1]
	v_cvt_scalef32_pk_fp4_f32 v65, v56, v57, 1.0 op_sel:[0,0,0,1]
	v_cvt_scalef32_pk_fp4_f32 v64, v54, v55, 1.0 op_sel:[0,0,1,1]
	v_cvt_scalef32_pk_fp4_f32 v65, v52, v53, 1.0 op_sel:[0,0,1,1]

; __device__ __forceinline__ void phase_prologue(CArgs& A, unsigned char* lds, int tid) {
;     ...
;         for (int u = 0; u < 4; ++u) { const int r = it + u * NGW; if (r < 2 * R_U) {
;             {
;                 const float V_SC = (r < R_U) ? U_SCALE : V_SCALE;
;                 unsigned char* dst = (r < R_U) ? (ws + WS_U + (size_t)r * DM - lane * 8 + lane * 16) : (ws + WS_U + (size_t)(r - R_U) * DM - lane * 8 + lane * 16 + 8);
;                 const f32x4 a0 = rv[u][0] * V_SC, a1 = rv[u][1] * V_SC, a2 = rv[u][2] * V_SC, a3 = rv[u][3] * V_SC;
;                 unsigned w0 = 0u, w1 = 0u;
;                 if (r < R_U) {
;                     const float av[16] = {a0.x, a0.y, a0.z, a0.w, a1.x, a1.y, a1.z, a1.w, a2.x, a2.y, a2.z, a2.w, a3.x, a3.y, a3.z, a3.w};
; #pragma unroll
;                     for (int i = 0; i < 8; ++i) { const int q0 = (int)fminf(fmaxf(rintf(av[i]), -7.f), 7.f), q1 = (int)fminf(fmaxf(rintf(av[8 + i]), -7.f), 7.f);
;                         w0 |= ((unsigned)q0 & 0xFu) << (4 * i); w1 |= ((unsigned)q1 & 0xFu) << (4 * i); }
;                 } else {
;                 w0 = __builtin_amdgcn_cvt_scalef32_pk_fp4_f32(w0, a0.x, a0.y, 1.0f, 0); w0 = __builtin_amdgcn_cvt_scalef32_pk_fp4_f32(w0, a0.z, a0.w, 1.0f, 1);
;                 w0 = __builtin_amdgcn_cvt_scalef32_pk_fp4_f32(w0, a1.x, a1.y, 1.0f, 2); w0 = __builtin_amdgcn_cvt_scalef32_pk_fp4_f32(w0, a1.z, a1.w, 1.0f, 3);
;                 w1 = __builtin_amdgcn_cvt_scalef32_pk_fp4_f32(w1, a2.x, a2.y, 1.0f, 0); w1 = __builtin_amdgcn_cvt_scalef32_pk_fp4_f32(w1, a2.z, a2.w, 1.0f, 1);
;                 w1 = __builtin_amdgcn_cvt_scalef32_pk_fp4_f32(w1, a3.x, a3.y, 1.0f, 2); w1 = __builtin_amdgcn_cvt_scalef32_pk_fp4_f32(w1, a3.z, a3.w, 1.0f, 3);
;                 }
;                 u32x2 o; o.x = w0; o.y = w1;
;                 *(u32x2*)(dst + lane * 8) = o;
.LBB0_548:
	s_waitcnt vmcnt(6)
	v_cmp_gt_i32_e64 s[42:43], s19, v80
	v_cmp_lt_i32_e64 s[40:41], s84, v80
	s_and_saveexec_b64 s[8:9], s[40:41]
	s_xor_b64 s[8:9], exec, s[8:9]
	v_add_u32_e32 v50, 0xffff8000, v80
	v_mov_b32_e32 v51, v0
	v_lshlrev_b64 v[50:51], 10, v[50:51]
	v_lshl_add_u64 v[50:51], v[72:73], 0, v[50:51]
	v_lshl_add_u64 v[50:51], v[50:51], 0, s[86:87]
	s_andn2_saveexec_b64 s[8:9], s[8:9]
	v_ashrrev_i32_e32 v81, 31, v80
	v_lshlrev_b64 v[50:51], 10, v[80:81]
	v_lshl_add_u64 v[50:51], v[74:75], 0, v[50:51]
	s_or_b64 exec, exec, s[8:9]
	v_cndmask_b32_e64 v56, v189, v190, s[42:43]
	v_pk_mul_f32 v[62:63], v[56:57], v[32:33] op_sel_hi:[0,1]
	v_pk_mul_f32 v[80:81], v[56:57], v[30:31] op_sel_hi:[0,1]
	v_pk_mul_f32 v[54:55], v[56:57], v[28:29] op_sel_hi:[0,1]
	v_pk_mul_f32 v[58:59], v[56:57], v[26:27] op_sel_hi:[0,1]
	v_pk_mul_f32 v[60:61], v[56:57], v[24:25] op_sel_hi:[0,1]
	v_pk_mul_f32 v[70:71], v[56:57], v[22:23] op_sel_hi:[0,1]
	v_pk_mul_f32 v[52:53], v[56:57], v[20:21] op_sel_hi:[0,1]
	v_pk_mul_f32 v[56:57], v[56:57], v[18:19] op_sel_hi:[0,1]
	s_and_saveexec_b64 s[8:9], s[40:41]
	s_xor_b64 s[8:9], exec, s[8:9]
	s_cbranch_execz .LBB0_554
	v_mov_b32_e32 v64, v0
	v_mov_b32_e32 v65, v0
	v_cvt_scalef32_pk_fp4_f32 v64, v80, v81, 1.0
	v_cvt_scalef32_pk_fp4_f32 v65, v70, v71, 1.0
	v_cvt_scalef32_pk_fp4_f32 v64, v62, v63, 1.0 op_sel:[0,0,1,0]
	v_cvt_scalef32_pk_fp4_f32 v65, v60, v61, 1.0 op_sel:[0,0,1,0]
	v_cvt_scalef32_pk_fp4_f32 v64, v58, v59, 1.0 op_sel:[0,0,0,1]
	v_cvt_scalef32_pk_fp4_f32 v65, v56, v57, 1.0 op_sel:[0,0,0,1]
	v_cvt_scalef32_pk_fp4_f32 v64, v54, v55, 1.0 op_sel:[0,0,1,1]
	v_cvt_scalef32_pk_fp4_f32 v65, v52, v53, 1.0 op_sel:[0,0,1,1]

; __device__ __forceinline__ void phase_prologue(CArgs& A, unsigned char* lds, int tid) {
;     ...
;         for (int u = 0; u < 4; ++u) { const int r = it + u * NGW; if (r < 2 * R_U) {
;             {
;                 const float V_SC = (r < R_U) ? U_SCALE : V_SCALE;
;                 unsigned char* dst = (r < R_U) ? (ws + WS_U + (size_t)r * DM - lane * 8 + lane * 16) : (ws + WS_U + (size_t)(r - R_U) * DM - lane * 8 + lane * 16 + 8);
;                 const f32x4 a0 = rv[u][0] * V_SC, a1 = rv[u][1] * V_SC, a2 = rv[u][2] * V_SC, a3 = rv[u][3] * V_SC;
;                 unsigned w0 = 0u, w1 = 0u;
;                 if (r < R_U) {
;                     const float av[16] = {a0.x, a0.y, a0.z, a0.w, a1.x, a1.y, a1.z, a1.w, a2.x, a2.y, a2.z, a2.w, a3.x, a3.y, a3.z, a3.w};
; #pragma unroll
;                     for (int i = 0; i < 8; ++i) { const int q0 = (int)fminf(fmaxf(rintf(av[i]), -7.f), 7.f), q1 = (int)fminf(fmaxf(rintf(av[8 + i]), -7.f), 7.f);
;                         w0 |= ((unsigned)q0 & 0xFu) << (4 * i); w1 |= ((unsigned)q1 & 0xFu) << (4 * i); }
;                 } else {
;                 w0 = __builtin_amdgcn_cvt_scalef32_pk_fp4_f32(w0, a0.x, a0.y, 1.0f, 0); w0 = __builtin_amdgcn_cvt_scalef32_pk_fp4_f32(w0, a0.z, a0.w, 1.0f, 1);
;                 w0 = __builtin_amdgcn_cvt_scalef32_pk_fp4_f32(w0, a1.x, a1.y, 1.0f, 2); w0 = __builtin_amdgcn_cvt_scalef32_pk_fp4_f32(w0, a1.z, a1.w, 1.0f, 3);
;                 w1 = __builtin_amdgcn_cvt_scalef32_pk_fp4_f32(w1, a2.x, a2.y, 1.0f, 0); w1 = __builtin_amdgcn_cvt_scalef32_pk_fp4_f32(w1, a2.z, a2.w, 1.0f, 1);
;                 w1 = __builtin_amdgcn_cvt_scalef32_pk_fp4_f32(w1, a3.x, a3.y, 1.0f, 2); w1 = __builtin_amdgcn_cvt_scalef32_pk_fp4_f32(w1, a3.z, a3.w, 1.0f, 3);
;                 }
;                 u32x2 o; o.x = w0; o.y = w1;
;                 *(u32x2*)(dst + lane * 8) = o;
.LBB0_557:
	s_waitcnt vmcnt(3)
	v_cmp_gt_i32_e64 s[40:41], s19, v78
	v_cmp_lt_i32_e32 vcc, s84, v78
	s_and_saveexec_b64 s[8:9], vcc
	s_xor_b64 s[8:9], exec, s[8:9]
	v_add_u32_e32 v50, 0xffff8000, v78
	v_mov_b32_e32 v51, v0
	v_lshlrev_b64 v[50:51], 10, v[50:51]
	v_lshl_add_u64 v[50:51], v[72:73], 0, v[50:51]
	v_lshl_add_u64 v[50:51], v[50:51], 0, s[86:87]
	s_andn2_saveexec_b64 s[8:9], s[8:9]
	v_ashrrev_i32_e32 v79, 31, v78
	v_lshlrev_b64 v[50:51], 10, v[78:79]
	v_lshl_add_u64 v[50:51], v[74:75], 0, v[50:51]
	s_or_b64 exec, exec, s[8:9]
	v_cndmask_b32_e64 v56, v189, v190, s[40:41]
	v_pk_mul_f32 v[62:63], v[56:57], v[16:17] op_sel_hi:[0,1]
	v_pk_mul_f32 v[78:79], v[56:57], v[14:15] op_sel_hi:[0,1]
	v_pk_mul_f32 v[54:55], v[56:57], v[12:13] op_sel_hi:[0,1]
	v_pk_mul_f32 v[58:59], v[56:57], v[10:11] op_sel_hi:[0,1]
	v_pk_mul_f32 v[60:61], v[56:57], v[8:9] op_sel_hi:[0,1]
	v_pk_mul_f32 v[70:71], v[56:57], v[6:7] op_sel_hi:[0,1]
	v_pk_mul_f32 v[52:53], v[56:57], v[4:5] op_sel_hi:[0,1]
	v_pk_mul_f32 v[56:57], v[56:57], v[2:3] op_sel_hi:[0,1]
	s_and_saveexec_b64 s[8:9], vcc
	s_xor_b64 s[8:9], exec, s[8:9]
	s_cbranch_execz .LBB0_563
	v_mov_b32_e32 v64, v0
	v_mov_b32_e32 v65, v0
	v_cvt_scalef32_pk_fp4_f32 v64, v78, v79, 1.0
	v_cvt_scalef32_pk_fp4_f32 v65, v70, v71, 1.0
	v_cvt_scalef32_pk_fp4_f32 v64, v62, v63, 1.0 op_sel:[0,0,1,0]
	v_cvt_scalef32_pk_fp4_f32 v65, v60, v61, 1.0 op_sel:[0,0,1,0]
	v_cvt_scalef32_pk_fp4_f32 v64, v58, v59, 1.0 op_sel:[0,0,0,1]
	v_cvt_scalef32_pk_fp4_f32 v65, v56, v57, 1.0 op_sel:[0,0,0,1]
	v_cvt_scalef32_pk_fp4_f32 v64, v54, v55, 1.0 op_sel:[0,0,1,1]
	v_cvt_scalef32_pk_fp4_f32 v65, v52, v53, 1.0 op_sel:[0,0,1,1]
